# LayerNorm passes: gamma/beta held in registers across the row loop (were re-loaded per row in 8 serialized pieces); vmcnt recounted so stores are not waited for
# speedup vs baseline: 1.0104x; 1.0093x over previous
.LBB0_977:
	s_cmp_lt_i32 s84, 9
	s_cselect_b64 s[4:5], -1, 0
	s_and_b64 s[6:7], s[4:5], s[0:1]
	s_andn2_b64 vcc, exec, s[6:7]
	s_cbranch_vccnz .LBB0_981
	s_cmpk_gt_i32 s72, 0x3fff
	s_cbranch_scc1 .LBB0_981
	v_mbcnt_hi_u32_b32 v2, -1, v148
	v_and_b32_e32 v1, 64, v2
	v_add_u32_e32 v3, 64, v1
	v_xor_b32_e32 v1, 1, v2
	v_cmp_lt_i32_e32 vcc, v1, v3
	v_xor_b32_e32 v4, 2, v2
	v_readlane_b32 s12, v239, 28
	v_cndmask_b32_e32 v1, v2, v1, vcc
	v_cmp_lt_i32_e32 vcc, v4, v3
	v_readlane_b32 s13, v239, 29
	v_readlane_b32 s14, v239, 30
	v_cndmask_b32_e32 v4, v2, v4, vcc
	v_lshlrev_b32_e32 v71, 2, v4
	v_xor_b32_e32 v4, 4, v2
	v_cmp_lt_i32_e32 vcc, v4, v3
	v_readlane_b32 s15, v239, 31
	v_readlane_b32 s16, v239, 32
	v_cndmask_b32_e32 v4, v2, v4, vcc
	v_lshlrev_b32_e32 v92, 2, v4
	v_xor_b32_e32 v4, 8, v2
	v_cmp_lt_i32_e32 vcc, v4, v3
	v_readlane_b32 s17, v239, 33
	v_readlane_b32 s18, v239, 34
	v_cndmask_b32_e32 v4, v2, v4, vcc
	v_lshlrev_b32_e32 v93, 2, v4
	v_xor_b32_e32 v4, 16, v2
	v_cmp_lt_i32_e32 vcc, v4, v3
	v_readlane_b32 s19, v239, 35
	v_readlane_b32 s12, v239, 0
	v_cndmask_b32_e32 v4, v2, v4, vcc
	v_lshlrev_b32_e32 v94, 2, v4
	v_xor_b32_e32 v4, 32, v2
	v_cmp_lt_i32_e32 vcc, v4, v3
	v_mov_b32_e32 v3, 0
	v_readlane_b32 s22, v239, 38
	v_cndmask_b32_e32 v2, v2, v4, vcc
	v_lshlrev_b32_e32 v95, 2, v2
	v_lshlrev_b32_e32 v2, 4, v152
	v_readlane_b32 s23, v239, 39
	v_readlane_b32 s26, v239, 42
	v_readlane_b32 s27, v239, 43
	v_readlane_b32 s13, v239, 1
	s_lshl_b32 s8, s72, 1
	s_mov_b64 s[22:23], s[26:27]
	s_mov_b64 s[4:5], s[12:13]
	v_or_b32_e32 v4, 0x1000, v2
	v_mov_b32_e32 v5, v3
	v_lshl_add_u64 v[38:39], s[22:23], 0, v[4:5]
	v_lshl_add_u64 v[40:41], s[4:5], 0, v[4:5]
	v_or_b32_e32 v4, 0x1400, v2
	s_ashr_i32 s9, s8, 31
	v_lshl_add_u64 v[42:43], s[22:23], 0, v[4:5]
	v_lshl_add_u64 v[44:45], s[4:5], 0, v[4:5]
	v_or_b32_e32 v4, 0x1800, v2
	s_lshl_b32 s10, s33, 4
	s_lshl_b64 s[0:1], s[8:9], 12
	v_readlane_b32 s20, v239, 36
	v_readlane_b32 s21, v239, 37
	v_readlane_b32 s24, v239, 40
	v_readlane_b32 s25, v239, 41
	v_readlane_b32 s16, v239, 4
	v_readlane_b32 s17, v239, 5
	v_readlane_b32 s18, v239, 6
	v_readlane_b32 s19, v239, 7
	s_waitcnt vmcnt(0)
	v_lshl_add_u64 v[46:47], s[22:23], 0, v[4:5]
	v_lshl_add_u64 v[48:49], s[4:5], 0, v[4:5]
	v_or_b32_e32 v4, 0x1c00, v2
	s_add_u32 s0, s78, s0
	v_lshl_add_u64 v[34:35], s[22:23], 0, v[2:3]
	v_lshl_add_u64 v[50:51], s[22:23], 0, v[4:5]
	v_lshl_add_u64 v[52:53], s[4:5], 0, v[4:5]
	v_lshlrev_b32_e32 v4, 3, v152
	s_addc_u32 s1, s79, s1
	v_readlane_b32 s16, v239, 10
	v_lshl_add_u64 v[4:5], s[0:1], 0, v[4:5]
	s_mov_b64 s[0:1], 0x30001e00
	s_ashr_i32 s11, s10, 31
	v_readlane_b32 s17, v239, 11
	v_lshl_add_u64 v[36:37], s[4:5], 0, v[2:3]
	v_lshl_add_u64 v[54:55], v[4:5], 0, s[0:1]
	s_lshl_b64 s[12:13], s[10:11], 12
	s_lshl_b64 s[0:1], s[8:9], 13
	s_mov_b64 s[4:5], s[16:17]
	s_add_u32 s0, s4, s0
	s_addc_u32 s1, s5, s1
	v_readlane_b32 s14, v239, 2
	v_readlane_b32 s15, v239, 3
	v_readlane_b32 s18, v239, 12
	v_readlane_b32 s19, v239, 13
	v_lshl_add_u64 v[2:3], s[0:1], 0, v[2:3]
	s_mov_b64 s[0:1], 0x2000
	v_lshlrev_b32_e32 v1, 2, v1
	s_movk_i32 s3, 0x1000
	v_lshl_add_u64 v[56:57], v[2:3], 0, s[0:1]
	s_lshl_b64 s[14:15], s[10:11], 13
	s_movk_i32 s9, 0xf000
	s_brev_b32 s11, 55
	s_mov_b32 s17, 0xffff0000
	s_mov_b32 s16, 0x3f9837f0
	v_mov_b32_e32 v96, 0x3727c5ac
	s_mov_b32 s18, 0xf800000
	v_mov_b32_e32 v97, 0x260
	s_movk_i32 s19, 0x7fff
	v_readlane_b32 s20, v239, 14
	v_readlane_b32 s21, v239, 15
	v_readlane_b32 s22, v239, 16
	v_readlane_b32 s23, v239, 17
	v_readlane_b32 s24, v239, 18
	v_readlane_b32 s25, v239, 19
	v_readlane_b32 s26, v239, 20
	v_readlane_b32 s27, v239, 21
	v_readlane_b32 s28, v239, 22
	v_readlane_b32 s29, v239, 23
	v_readlane_b32 s30, v239, 24
	v_readlane_b32 s31, v239, 25
	global_load_dwordx4 v[160:163], v[34:35], off
	global_load_dwordx4 v[164:167], v[36:37], off
	global_load_dwordx4 v[168:171], v[34:35], off offset:1024
	global_load_dwordx4 v[172:175], v[36:37], off offset:1024
	global_load_dwordx4 v[176:179], v[34:35], off offset:2048
	global_load_dwordx4 v[180:183], v[36:37], off offset:2048
	global_load_dwordx4 v[184:187], v[34:35], off offset:3072
	global_load_dwordx4 v[188:191], v[36:37], off offset:3072
	global_load_dwordx4 v[192:195], v[38:39], off
	global_load_dwordx4 v[196:199], v[40:41], off
	global_load_dwordx4 v[200:203], v[42:43], off
	global_load_dwordx4 v[204:207], v[44:45], off
	global_load_dwordx4 v[208:211], v[46:47], off
	global_load_dwordx4 v[212:215], v[48:49], off
	global_load_dwordx4 v[216:219], v[50:51], off
	global_load_dwordx4 v[220:223], v[52:53], off
	s_waitcnt vmcnt(0)
.LBB0_980:
	v_add_co_u32_e32 v58, vcc, 0xebfff000, v54
	v_add_co_u32_e64 v108, s[4:5], s3, v56
	s_nop 0
	v_addc_co_u32_e32 v59, vcc, -1, v55, vcc
	v_add_co_u32_e32 v6, vcc, 0xffffe000, v56
	global_load_dwordx2 v[60:61], v[58:59], off offset:-3584 nt
	global_load_dwordx2 v[62:63], v[58:59], off offset:-3072 nt
	global_load_dwordx2 v[64:65], v[58:59], off offset:-2560 nt
	global_load_dwordx2 v[66:67], v[58:59], off offset:-2048 nt
	global_load_dwordx4 v[2:5], v[56:57], off offset:-4096 nt
	global_load_dwordx2 v[68:69], v[58:59], off offset:-1536 nt
	v_addc_co_u32_e32 v7, vcc, -1, v57, vcc
	global_load_dwordx4 v[6:9], v[6:7], off nt
	v_add_co_u32_e32 v74, vcc, 0xfffff000, v56
	global_load_dwordx2 v[72:73], v[58:59], off offset:-1024 nt
	s_nop 0
	v_addc_co_u32_e32 v75, vcc, -1, v57, vcc
	global_load_dwordx4 v[10:13], v[74:75], off offset:-3072 nt
	global_load_dwordx4 v[14:17], v[74:75], off offset:-2048 nt
	global_load_dwordx4 v[18:21], v[74:75], off offset:-1024 nt
	global_load_dwordx4 v[22:25], v[56:57], off offset:-3072 nt
	global_load_dwordx2 v[98:99], v[58:59], off offset:-512 nt
	global_load_dwordx4 v[26:29], v[56:57], off offset:-2048 nt
	global_load_dwordx2 v[100:101], v[58:59], off nt
	global_load_dwordx4 v[30:33], v[56:57], off offset:-1024 nt
	v_addc_co_u32_e64 v109, s[4:5], 0, v57, s[4:5]
	s_add_i32 s8, s8, s10
	s_cmp_lt_i32 s8, 0x8000
	s_waitcnt vmcnt(0)
	v_lshlrev_b32_e32 v58, 16, v60
	v_and_b32_e32 v59, 0xffff0000, v60
	v_lshlrev_b32_e32 v60, 16, v61
	v_and_b32_e32 v61, 0xffff0000, v61
	v_lshlrev_b32_e32 v78, 16, v62
	v_and_b32_e32 v79, 0xffff0000, v62
	v_lshlrev_b32_e32 v62, 16, v63
	v_and_b32_e32 v63, 0xffff0000, v63
	v_lshlrev_b32_e32 v80, 16, v64
	v_and_b32_e32 v81, 0xffff0000, v64
	v_lshlrev_b32_e32 v64, 16, v65
	v_and_b32_e32 v65, 0xffff0000, v65
	v_lshlrev_b32_e32 v74, 16, v68
	v_and_b32_e32 v75, 0xffff0000, v68
	v_lshlrev_b32_e32 v68, 16, v69
	v_and_b32_e32 v69, 0xffff0000, v69
	v_pk_fma_f32 v[76:77], v[8:9], s[16:17], v[60:61] op_sel_hi:[1,0,1]
	v_pk_fma_f32 v[90:91], v[6:7], s[16:17], v[58:59] op_sel_hi:[1,0,1]
	v_pk_fma_f32 v[86:87], v[12:13], s[16:17], v[62:63] op_sel_hi:[1,0,1]
	v_pk_fma_f32 v[88:89], v[10:11], s[16:17], v[78:79] op_sel_hi:[1,0,1]
	v_lshlrev_b32_e32 v102, 16, v66
	v_and_b32_e32 v103, 0xffff0000, v66
	v_lshlrev_b32_e32 v104, 16, v72
	v_and_b32_e32 v105, 0xffff0000, v72
	v_lshlrev_b32_e32 v106, 16, v73
	v_and_b32_e32 v107, 0xffff0000, v73
	v_pk_fma_f32 v[72:73], v[4:5], s[16:17], v[68:69] op_sel_hi:[1,0,1]
	v_pk_fma_f32 v[74:75], v[2:3], s[16:17], v[74:75] op_sel_hi:[1,0,1]
	v_mov_b32_e32 v2, v90
	v_mov_b32_e32 v4, v91
	v_mov_b32_e32 v6, v76
	v_mov_b32_e32 v8, v77
	v_pk_fma_f32 v[82:83], v[16:17], s[16:17], v[64:65] op_sel_hi:[1,0,1]
	v_pk_fma_f32 v[84:85], v[14:15], s[16:17], v[80:81] op_sel_hi:[1,0,1]
	v_mov_b32_e32 v3, v88
	v_mov_b32_e32 v5, v89
	v_mov_b32_e32 v7, v86
	v_mov_b32_e32 v9, v87
	v_pk_fma_f32 v[80:81], v[18:19], s[16:17], v[102:103] op_sel_hi:[1,0,1]
	v_pk_mov_b32 v[16:17], v[84:85], v[82:83] op_sel:[1,0]
	v_mov_b32_e32 v18, v84
	v_mov_b32_e32 v19, v83
	v_pk_add_f32 v[2:3], v[2:3], v[4:5]
	v_pk_add_f32 v[4:5], v[6:7], v[8:9]
	v_lshlrev_b32_e32 v66, 16, v67
	v_and_b32_e32 v67, 0xffff0000, v67
	v_pk_add_f32 v[6:7], v[16:17], v[18:19]
	v_pk_add_f32 v[2:3], v[2:3], v[4:5]
	v_pk_fma_f32 v[78:79], v[20:21], s[16:17], v[66:67] op_sel_hi:[1,0,1]
	v_pk_add_f32 v[4:5], v[6:7], v[6:7] op_sel:[0,1] op_sel_hi:[1,0]
	v_add_f32_e32 v2, 0, v2
	v_mov_b32_e32 v11, v74
	v_mov_b32_e32 v13, v72
	v_mov_b32_e32 v15, v73
	v_add_f32_e32 v12, v80, v81
	v_add_f32_e32 v14, v78, v79
	v_mov_b32_e32 v5, v75
	v_add_f32_e32 v10, v2, v3
	v_pk_fma_f32 v[66:67], v[24:25], s[16:17], v[106:107] op_sel_hi:[1,0,1]
	v_pk_fma_f32 v[68:69], v[22:23], s[16:17], v[104:105] op_sel_hi:[1,0,1]
	v_pk_add_f32 v[8:9], v[12:13], v[14:15]
	v_pk_add_f32 v[2:3], v[10:11], v[4:5]
	v_pk_mov_b32 v[4:5], v[68:69], v[66:67] op_sel:[1,0]
	v_mov_b32_e32 v6, v68
	v_mov_b32_e32 v7, v67
	v_pk_add_f32 v[2:3], v[2:3], v[8:9]
	v_pk_add_f32 v[4:5], v[4:5], v[6:7]
	v_lshlrev_b32_e32 v6, 16, v98
	v_and_b32_e32 v7, 0xffff0000, v98
	v_lshlrev_b32_e32 v8, 16, v99
	v_and_b32_e32 v9, 0xffff0000, v99
	v_lshlrev_b32_e32 v10, 16, v100
	v_and_b32_e32 v11, 0xffff0000, v100
	v_lshlrev_b32_e32 v12, 16, v101
	v_and_b32_e32 v13, 0xffff0000, v101
	v_pk_add_f32 v[2:3], v[2:3], v[2:3] op_sel:[0,1] op_sel_hi:[1,0]
	v_pk_add_f32 v[4:5], v[4:5], v[4:5] op_sel:[0,1] op_sel_hi:[1,0]
	v_pk_fma_f32 v[62:63], v[28:29], s[16:17], v[8:9] op_sel_hi:[1,0,1]
	v_pk_fma_f32 v[64:65], v[26:27], s[16:17], v[6:7] op_sel_hi:[1,0,1]
	v_pk_fma_f32 v[58:59], v[32:33], s[16:17], v[12:13] op_sel_hi:[1,0,1]
	v_pk_fma_f32 v[60:61], v[30:31], s[16:17], v[10:11] op_sel_hi:[1,0,1]
	v_add_f32_e32 v6, v64, v65
	v_add_f32_e32 v8, v62, v63
	v_mov_b32_e32 v3, v60
	v_mov_b32_e32 v5, v61
	v_mov_b32_e32 v7, v58
	v_mov_b32_e32 v9, v59
	v_pk_add_f32 v[2:3], v[2:3], v[4:5]
	v_pk_add_f32 v[4:5], v[6:7], v[8:9]
	v_mov_b32_e32 v98, v160
	v_mov_b32_e32 v99, v161
	v_mov_b32_e32 v100, v162
	v_mov_b32_e32 v101, v163
	v_mov_b32_e32 v102, v164
	v_mov_b32_e32 v103, v165
	v_mov_b32_e32 v104, v166
	v_mov_b32_e32 v105, v167
	v_pk_add_f32 v[2:3], v[2:3], v[4:5]
	v_add_co_u32_e32 v106, vcc, s11, v54
	v_add_f32_e32 v2, v2, v3
	ds_bpermute_b32 v3, v1, v2
	s_mov_b64 s[0:1], vcc
	s_waitcnt lgkmcnt(0)
	v_add_f32_e32 v2, v2, v3
	ds_bpermute_b32 v3, v71, v2
	s_waitcnt lgkmcnt(0)
	v_add_f32_e32 v2, v2, v3
	ds_bpermute_b32 v3, v92, v2
	s_waitcnt lgkmcnt(0)
	v_add_f32_e32 v2, v2, v3
	ds_bpermute_b32 v3, v93, v2
	s_waitcnt lgkmcnt(0)
	v_add_f32_e32 v2, v2, v3
	ds_bpermute_b32 v3, v94, v2
	s_waitcnt lgkmcnt(0)
	v_add_f32_e32 v2, v2, v3
	ds_bpermute_b32 v3, v95, v2
	s_waitcnt lgkmcnt(0)
	v_add_f32_e32 v10, v2, v3
	v_fmamk_f32 v91, v10, 0xba000000, v91
	v_fmamk_f32 v89, v10, 0xba000000, v89
	v_fmamk_f32 v77, v10, 0xba000000, v77
	v_fmac_f32_e32 v90, 0xba000000, v10
	v_fmamk_f32 v87, v10, 0xba000000, v87
	v_fmac_f32_e32 v88, 0xba000000, v10
	v_mov_b32_e32 v4, v91
	v_mov_b32_e32 v5, v89
	v_fmac_f32_e32 v76, 0xba000000, v10
	v_fmac_f32_e32 v86, 0xba000000, v10
	v_mov_b32_e32 v2, v90
	v_mov_b32_e32 v3, v88
	v_pk_mul_f32 v[4:5], v[4:5], v[4:5]
	v_mov_b32_e32 v6, v77
	v_mov_b32_e32 v7, v87
	v_pk_fma_f32 v[2:3], v[2:3], v[2:3], v[4:5]
	v_mov_b32_e32 v4, v76
	v_mov_b32_e32 v5, v86
	v_pk_mul_f32 v[6:7], v[6:7], v[6:7]
	v_fmamk_f32 v85, v10, 0xba000000, v85
	v_pk_fma_f32 v[4:5], v[4:5], v[4:5], v[6:7]
	v_fmac_f32_e32 v84, 0xba000000, v10
	v_pk_add_f32 v[2:3], v[2:3], v[4:5]
	v_fmamk_f32 v83, v10, 0xba000000, v83
	v_fmac_f32_e32 v82, 0xba000000, v10
	v_pk_add_f32 v[2:3], v[2:3], v[2:3] op_sel_hi:[0,1]
	v_pk_mul_f32 v[4:5], v[82:83], v[82:83]
	v_pk_mul_f32 v[6:7], v[84:85], v[84:85]
	v_fmac_f32_e32 v80, 0xba000000, v10
	v_pk_mov_b32 v[8:9], v[6:7], v[4:5] op_sel:[1,0]
	v_mov_b32_e32 v7, v5
	v_fmamk_f32 v81, v10, 0xba000000, v81
	v_fmac_f32_e32 v78, 0xba000000, v10
	v_mul_f32_e32 v2, v80, v80
	v_pk_add_f32 v[4:5], v[8:9], v[6:7]
	v_fmamk_f32 v79, v10, 0xba000000, v79
	v_pk_fma_f32 v[6:7], v[80:81], v[80:81], v[2:3] op_sel_hi:[1,1,0]
	v_mul_f32_e32 v2, v78, v78
	v_pk_add_f32 v[4:5], v[4:5], v[4:5] op_sel_hi:[0,1]
	v_pk_fma_f32 v[8:9], v[78:79], v[78:79], v[2:3] op_sel_hi:[1,1,0]
	v_fmamk_f32 v73, v10, 0xba000000, v73
	v_fmac_f32_e32 v72, 0xba000000, v10
	v_fmamk_f32 v75, v10, 0xba000000, v75
	v_fmac_f32_e32 v74, 0xba000000, v10
	v_mul_f32_e32 v6, v74, v74
	v_mul_f32_e32 v8, v75, v75
	v_mul_f32_e32 v4, v72, v72
	v_mul_f32_e32 v2, v73, v73
	v_pk_add_f32 v[6:7], v[6:7], v[8:9]
	v_pk_add_f32 v[2:3], v[4:5], v[2:3]
	v_fmamk_f32 v69, v10, 0xba000000, v69
	v_pk_add_f32 v[2:3], v[6:7], v[2:3]
	v_fmac_f32_e32 v68, 0xba000000, v10
	v_fmamk_f32 v67, v10, 0xba000000, v67
	v_fmac_f32_e32 v66, 0xba000000, v10
	v_pk_add_f32 v[2:3], v[2:3], v[2:3] op_sel_hi:[0,1]
	v_pk_mul_f32 v[4:5], v[66:67], v[66:67]
	v_pk_mul_f32 v[6:7], v[68:69], v[68:69]
	v_fmac_f32_e32 v64, 0xba000000, v10
	v_pk_mov_b32 v[8:9], v[6:7], v[4:5] op_sel:[1,0]
	v_mov_b32_e32 v7, v5
	v_fmamk_f32 v65, v10, 0xba000000, v65
	v_fmac_f32_e32 v62, 0xba000000, v10
	v_mul_f32_e32 v2, v64, v64
	v_pk_add_f32 v[4:5], v[8:9], v[6:7]
	v_fmamk_f32 v63, v10, 0xba000000, v63
	v_pk_fma_f32 v[6:7], v[64:65], v[64:65], v[2:3] op_sel_hi:[1,1,0]
	v_mul_f32_e32 v2, v62, v62
	v_pk_add_f32 v[4:5], v[4:5], v[4:5] op_sel_hi:[0,1]
	v_pk_fma_f32 v[8:9], v[62:63], v[62:63], v[2:3] op_sel_hi:[1,1,0]
	v_fmamk_f32 v59, v10, 0xba000000, v59
	v_fmac_f32_e32 v58, 0xba000000, v10
	v_fmamk_f32 v61, v10, 0xba000000, v61
	v_fmac_f32_e32 v60, 0xba000000, v10
	v_mul_f32_e32 v6, v60, v60
	v_mul_f32_e32 v8, v61, v61
	v_mul_f32_e32 v4, v58, v58
	v_mul_f32_e32 v2, v59, v59
	v_pk_add_f32 v[6:7], v[6:7], v[8:9]
	v_pk_add_f32 v[2:3], v[4:5], v[2:3]
	s_nop 0
	v_pk_add_f32 v[2:3], v[6:7], v[2:3]
	global_load_dwordx4 v[22:25], v[56:57], off nt
	global_load_dwordx4 v[18:21], v[56:57], off offset:1024 nt
	global_load_dwordx4 v[14:17], v[56:57], off offset:2048 nt
	global_load_dwordx4 v[6:9], v[56:57], off offset:3072 nt
	v_add_f32_e32 v2, v2, v3
	ds_bpermute_b32 v3, v1, v2
	v_lshl_add_u64 v[56:57], v[56:57], 0, s[14:15]
	s_waitcnt lgkmcnt(0)
	v_add_f32_e32 v2, v2, v3
	ds_bpermute_b32 v3, v71, v2
	s_waitcnt lgkmcnt(0)
	v_add_f32_e32 v2, v2, v3
	ds_bpermute_b32 v3, v92, v2
	s_waitcnt lgkmcnt(0)
	v_add_f32_e32 v2, v2, v3
	ds_bpermute_b32 v3, v93, v2
	s_waitcnt lgkmcnt(0)
	v_add_f32_e32 v2, v2, v3
	ds_bpermute_b32 v3, v94, v2
	s_waitcnt lgkmcnt(0)
	v_add_f32_e32 v2, v2, v3
	ds_bpermute_b32 v3, v95, v2
	s_waitcnt lgkmcnt(0)
	v_add_f32_e32 v2, v2, v3
	v_fmamk_f32 v2, v2, 0x3a000000, v96
	v_mul_f32_e32 v3, 0x4f800000, v2
	v_cmp_gt_f32_e32 vcc, s18, v2
	s_nop 1
	v_cndmask_b32_e32 v2, v2, v3, vcc
	v_sqrt_f32_e32 v3, v2
	s_nop 0
	v_add_u32_e32 v4, -1, v3
	v_fma_f32 v5, -v4, v3, v2
	v_cmp_ge_f32_e64 s[4:5], 0, v5
	v_add_u32_e32 v5, 1, v3
	s_nop 0
	v_cndmask_b32_e64 v4, v3, v4, s[4:5]
	v_fma_f32 v3, -v5, v3, v2
	v_cmp_lt_f32_e64 s[4:5], 0, v3
	s_nop 1
	v_cndmask_b32_e64 v3, v4, v5, s[4:5]
	v_mul_f32_e32 v4, 0x37800000, v3
	v_cndmask_b32_e32 v3, v3, v4, vcc
	v_cmp_class_f32_e32 vcc, v2, v97
	s_nop 1
	v_cndmask_b32_e32 v70, v3, v2, vcc
	v_div_scale_f32 v107, s[4:5], v70, v70, 1.0
	v_rcp_f32_e32 v110, v107
	global_load_dwordx4 v[30:33], v[108:109], off nt
	global_load_dwordx4 v[26:29], v[108:109], off offset:1024 nt
	global_load_dwordx4 v[10:13], v[108:109], off offset:2048 nt
	global_load_dwordx4 v[2:5], v[108:109], off offset:3072 nt
	v_fma_f32 v108, -v107, v110, 1.0
	v_fmac_f32_e32 v110, v108, v110
	v_div_scale_f32 v108, vcc, 1.0, v70, 1.0
	v_mul_f32_e32 v109, v108, v110
	v_fma_f32 v111, -v107, v109, v108
	v_fmac_f32_e32 v109, v111, v110
	v_fma_f32 v107, -v107, v109, v108
	v_div_fmas_f32 v107, v107, v110, v109
	v_div_fixup_f32 v70, v107, v70, 1.0
	v_pk_mul_f32 v[90:91], v[90:91], v[70:71] op_sel_hi:[1,0]
	v_pk_mul_f32 v[76:77], v[76:77], v[70:71] op_sel_hi:[1,0]
	s_waitcnt vmcnt(8)
	v_pk_fma_f32 v[90:91], v[98:99], v[90:91], v[102:103]
	v_pk_fma_f32 v[76:77], v[100:101], v[76:77], v[104:105]
	v_bfe_u32 v98, v90, 16, 1
	v_add3_u32 v90, v90, v98, s19
	v_bfe_u32 v98, v91, 16, 1
	v_lshrrev_b32_e32 v90, 16, v90
	v_add3_u32 v91, v91, v98, s19
	v_and_or_b32 v90, v91, s17, v90
	v_bfe_u32 v91, v76, 16, 1
	v_add3_u32 v76, v76, v91, s19
	v_bfe_u32 v91, v77, 16, 1
	v_lshrrev_b32_e32 v76, 16, v76
	v_add3_u32 v77, v77, v91, s19
	v_and_or_b32 v91, v77, s17, v76
	v_add_co_u32_e32 v76, vcc, s9, v54
	v_pk_mul_f32 v[88:89], v[88:89], v[70:71] op_sel_hi:[1,0]
	s_nop 0
	v_addc_co_u32_e32 v77, vcc, -1, v55, vcc
	global_store_dwordx2 v[76:77], v[90:91], off offset:-3584 nt
	v_mov_b32_e32 v98, v168
	v_mov_b32_e32 v99, v169
	v_mov_b32_e32 v100, v170
	v_mov_b32_e32 v101, v171
	v_mov_b32_e32 v102, v172
	v_mov_b32_e32 v103, v173
	v_mov_b32_e32 v104, v174
	v_mov_b32_e32 v105, v175
	v_pk_mul_f32 v[86:87], v[86:87], v[70:71] op_sel_hi:[1,0]
	v_pk_mul_f32 v[84:85], v[84:85], v[70:71] op_sel_hi:[1,0]
	v_pk_mul_f32 v[82:83], v[82:83], v[70:71] op_sel_hi:[1,0]
	v_pk_mul_f32 v[80:81], v[80:81], v[70:71] op_sel_hi:[1,0]
	v_pk_mul_f32 v[78:79], v[78:79], v[70:71] op_sel_hi:[1,0]
	v_pk_mul_f32 v[74:75], v[74:75], v[70:71] op_sel_hi:[1,0]
	v_pk_mul_f32 v[72:73], v[72:73], v[70:71] op_sel_hi:[1,0]
	v_addc_co_u32_e64 v107, vcc, -1, v55, s[0:1]
	s_waitcnt vmcnt(1)
	v_pk_fma_f32 v[88:89], v[98:99], v[88:89], v[102:103]
	s_nop 0
	v_bfe_u32 v90, v88, 16, 1
	v_add3_u32 v88, v88, v90, s19
	v_bfe_u32 v90, v89, 16, 1
	v_pk_fma_f32 v[86:87], v[100:101], v[86:87], v[104:105]
	v_lshrrev_b32_e32 v88, 16, v88
	v_add3_u32 v89, v89, v90, s19
	v_and_or_b32 v88, v89, s17, v88
	v_bfe_u32 v89, v86, 16, 1
	v_add3_u32 v86, v86, v89, s19
	v_bfe_u32 v89, v87, 16, 1
	v_lshrrev_b32_e32 v86, 16, v86
	v_add3_u32 v87, v87, v89, s19
	v_and_or_b32 v89, v87, s17, v86
	global_store_dwordx2 v[76:77], v[88:89], off offset:-3072 nt
	v_mov_b32_e32 v86, v176
	v_mov_b32_e32 v87, v177
	v_mov_b32_e32 v88, v178
	v_mov_b32_e32 v89, v179
	s_nop 0
	v_mov_b32_e32 v98, v180
	v_mov_b32_e32 v99, v181
	v_mov_b32_e32 v100, v182
	v_mov_b32_e32 v101, v183
	s_waitcnt vmcnt(2)
	v_pk_fma_f32 v[82:83], v[88:89], v[82:83], v[100:101]
	v_pk_fma_f32 v[84:85], v[86:87], v[84:85], v[98:99]
	v_bfe_u32 v88, v82, 16, 1
	v_bfe_u32 v86, v84, 16, 1
	v_bfe_u32 v87, v85, 16, 1
	v_bfe_u32 v89, v83, 16, 1
	v_add3_u32 v84, v84, v86, s19
	v_add3_u32 v82, v82, v88, s19
	v_add3_u32 v85, v85, v87, s19
	v_add3_u32 v83, v83, v89, s19
	v_lshrrev_b32_e32 v84, 16, v84
	v_lshrrev_b32_e32 v86, 16, v82
	v_and_or_b32 v82, v85, s17, v84
	v_and_or_b32 v83, v83, s17, v86
	global_store_dwordx2 v[76:77], v[82:83], off offset:-2560 nt
	v_mov_b32_e32 v82, v184
	v_mov_b32_e32 v83, v185
	v_mov_b32_e32 v84, v186
	v_mov_b32_e32 v85, v187
	s_nop 0
	v_mov_b32_e32 v86, v188
	v_mov_b32_e32 v87, v189
	v_mov_b32_e32 v88, v190
	v_mov_b32_e32 v89, v191
	s_waitcnt vmcnt(3)
	v_pk_fma_f32 v[78:79], v[84:85], v[78:79], v[88:89]
	v_pk_fma_f32 v[80:81], v[82:83], v[80:81], v[86:87]
	v_bfe_u32 v84, v78, 16, 1
	v_bfe_u32 v82, v80, 16, 1
	v_bfe_u32 v83, v81, 16, 1
	v_bfe_u32 v85, v79, 16, 1
	v_add3_u32 v80, v80, v82, s19
	v_add3_u32 v78, v78, v84, s19
	v_add3_u32 v81, v81, v83, s19
	v_add3_u32 v79, v79, v85, s19
	v_lshrrev_b32_e32 v80, 16, v80
	v_lshrrev_b32_e32 v82, 16, v78
	v_and_or_b32 v78, v81, s17, v80
	v_and_or_b32 v79, v79, s17, v82
	global_store_dwordx2 v[76:77], v[78:79], off offset:-2048 nt
	v_mov_b32_e32 v78, v192
	v_mov_b32_e32 v79, v193
	v_mov_b32_e32 v80, v194
	v_mov_b32_e32 v81, v195
	s_nop 0
	v_mov_b32_e32 v82, v196
	v_mov_b32_e32 v83, v197
	v_mov_b32_e32 v84, v198
	v_mov_b32_e32 v85, v199
	global_load_dwordx2 v[90:91], v[106:107], off offset:-3584 nt
	global_load_dwordx2 v[102:103], v[106:107], off offset:-3072 nt
	global_load_dwordx2 v[104:105], v[106:107], off offset:-2560 nt
	global_load_dwordx2 v[108:109], v[106:107], off offset:-2048 nt
	global_load_dwordx2 v[110:111], v[106:107], off offset:-1536 nt
	global_load_dwordx2 v[112:113], v[106:107], off offset:-1024 nt
	global_load_dwordx2 v[114:115], v[106:107], off offset:-512 nt
	global_load_dwordx2 v[116:117], v[106:107], off nt
	s_waitcnt vmcnt(4)
	v_lshlrev_b32_e32 v106, 16, v109
	v_and_b32_e32 v107, 0xffff0000, v109
	s_waitcnt vmcnt(2)
	v_lshlrev_b32_e32 v118, 16, v112
	v_pk_fma_f32 v[72:73], v[80:81], v[72:73], v[84:85]
	v_pk_fma_f32 v[74:75], v[78:79], v[74:75], v[82:83]
	v_bfe_u32 v80, v72, 16, 1
	v_bfe_u32 v78, v74, 16, 1
	v_bfe_u32 v79, v75, 16, 1
	v_bfe_u32 v81, v73, 16, 1
	v_add3_u32 v74, v74, v78, s19
	v_add3_u32 v72, v72, v80, s19
	v_add3_u32 v75, v75, v79, s19
	v_add3_u32 v73, v73, v81, s19
	v_lshrrev_b32_e32 v74, 16, v74
	v_lshrrev_b32_e32 v78, 16, v72
	v_and_or_b32 v72, v75, s17, v74
	v_and_or_b32 v73, v73, s17, v78
	global_store_dwordx2 v[76:77], v[72:73], off offset:-1536 nt
	v_mov_b32_e32 v86, v200
	v_mov_b32_e32 v87, v201
	v_mov_b32_e32 v88, v202
	v_mov_b32_e32 v89, v203
	v_mov_b32_e32 v98, v204
	v_mov_b32_e32 v99, v205
	v_mov_b32_e32 v100, v206
	v_mov_b32_e32 v101, v207
	v_lshlrev_b32_e32 v72, 16, v90
	v_and_b32_e32 v73, 0xffff0000, v90
	v_lshlrev_b32_e32 v74, 16, v91
	v_and_b32_e32 v75, 0xffff0000, v91
	v_lshlrev_b32_e32 v80, 16, v102
	v_and_b32_e32 v81, 0xffff0000, v102
	v_lshlrev_b32_e32 v78, 16, v103
	v_and_b32_e32 v79, 0xffff0000, v103
	v_lshlrev_b32_e32 v90, 16, v104
	v_and_b32_e32 v91, 0xffff0000, v104
	v_lshlrev_b32_e32 v102, 16, v105
	v_and_b32_e32 v103, 0xffff0000, v105
	v_lshlrev_b32_e32 v104, 16, v108
	v_and_b32_e32 v105, 0xffff0000, v108
	s_waitcnt vmcnt(2)
	v_lshlrev_b32_e32 v120, 16, v114
	v_and_b32_e32 v121, 0xffff0000, v114
	v_lshlrev_b32_e32 v114, 16, v115
	v_and_b32_e32 v115, 0xffff0000, v115
	v_pk_fma_f32 v[82:83], v[24:25], s[16:17], v[74:75] op_sel_hi:[1,0,1]
	v_pk_fma_f32 v[84:85], v[22:23], s[16:17], v[72:73] op_sel_hi:[1,0,1]
	v_pk_fma_f32 v[22:23], v[8:9], s[16:17], v[106:107] op_sel_hi:[1,0,1]
	v_pk_fma_f32 v[24:25], v[6:7], s[16:17], v[104:105] op_sel_hi:[1,0,1]
	v_pk_fma_f32 v[6:7], v[12:13], s[16:17], v[114:115] op_sel_hi:[1,0,1]
	v_pk_mul_f32 v[8:9], v[68:69], v[70:71] op_sel_hi:[1,0]
	v_pk_mul_f32 v[12:13], v[66:67], v[70:71] op_sel_hi:[1,0]
	v_and_b32_e32 v119, 0xffff0000, v112
	v_lshlrev_b32_e32 v112, 16, v113
	v_and_b32_e32 v113, 0xffff0000, v113
	v_pk_fma_f32 v[72:73], v[16:17], s[16:17], v[102:103] op_sel_hi:[1,0,1]
	v_pk_fma_f32 v[74:75], v[14:15], s[16:17], v[90:91] op_sel_hi:[1,0,1]
	v_pk_fma_f32 v[14:15], v[28:29], s[16:17], v[112:113] op_sel_hi:[1,0,1]
	v_pk_fma_f32 v[16:17], v[26:27], s[16:17], v[118:119] op_sel_hi:[1,0,1]
	v_lshlrev_b32_e32 v108, 16, v110
	v_and_b32_e32 v109, 0xffff0000, v110
	v_lshlrev_b32_e32 v110, 16, v111
	v_and_b32_e32 v111, 0xffff0000, v111
	v_pk_fma_f32 v[78:79], v[20:21], s[16:17], v[78:79] op_sel_hi:[1,0,1]
	v_pk_fma_f32 v[80:81], v[18:19], s[16:17], v[80:81] op_sel_hi:[1,0,1]
	v_pk_fma_f32 v[18:19], v[32:33], s[16:17], v[110:111] op_sel_hi:[1,0,1]
	v_pk_fma_f32 v[20:21], v[30:31], s[16:17], v[108:109] op_sel_hi:[1,0,1]
	v_mov_b32_e32 v66, v82
	v_mov_b32_e32 v67, v78
	v_mov_b32_e32 v68, v83
	v_mov_b32_e32 v69, v79
	v_add_f32_e32 v90, v24, v25
	v_mov_b32_e32 v91, v18
	v_pk_mov_b32 v[102:103], v[16:17], v[14:15] op_sel:[1,0]
	v_mov_b32_e32 v104, v16
	v_mov_b32_e32 v105, v15
	s_waitcnt vmcnt(1)
	v_lshlrev_b32_e32 v122, 16, v116
	v_and_b32_e32 v123, 0xffff0000, v116
	v_lshlrev_b32_e32 v116, 16, v117
	v_and_b32_e32 v117, 0xffff0000, v117
	v_pk_fma_f32 v[4:5], v[4:5], s[16:17], v[116:117] op_sel_hi:[1,0,1]
	v_pk_fma_f32 v[2:3], v[2:3], s[16:17], v[122:123] op_sel_hi:[1,0,1]
	v_add_f32_e32 v108, v6, v7
	v_mov_b32_e32 v107, v4
	v_mov_b32_e32 v109, v5
	s_waitcnt vmcnt(1)
	v_pk_fma_f32 v[12:13], v[88:89], v[12:13], v[100:101]
	v_pk_fma_f32 v[8:9], v[86:87], v[8:9], v[98:99]
	v_bfe_u32 v28, v12, 16, 1
	v_bfe_u32 v26, v8, 16, 1
	v_bfe_u32 v27, v9, 16, 1
	v_bfe_u32 v29, v13, 16, 1
	v_add3_u32 v8, v8, v26, s19
	v_add3_u32 v12, v12, v28, s19
	v_add3_u32 v9, v9, v27, s19
	v_add3_u32 v13, v13, v29, s19
	v_lshrrev_b32_e32 v8, 16, v8
	v_lshrrev_b32_e32 v12, 16, v12
	v_and_or_b32 v8, v9, s17, v8
	v_and_or_b32 v9, v13, s17, v12
	global_store_dwordx2 v[76:77], v[8:9], off offset:-1024 nt
	v_mov_b32_e32 v26, v208
	v_mov_b32_e32 v27, v209
	v_mov_b32_e32 v28, v210
	v_mov_b32_e32 v29, v211
	v_mov_b32_e32 v30, v212
	v_mov_b32_e32 v31, v213
	v_mov_b32_e32 v32, v214
	v_mov_b32_e32 v33, v215
	v_pk_fma_f32 v[8:9], v[10:11], s[16:17], v[120:121] op_sel_hi:[1,0,1]
	v_mov_b32_e32 v10, v84
	v_mov_b32_e32 v11, v80
	v_mov_b32_e32 v12, v85
	v_mov_b32_e32 v13, v81
	v_pk_mov_b32 v[86:87], v[74:75], v[72:73] op_sel:[1,0]
	v_mov_b32_e32 v88, v74
	v_mov_b32_e32 v89, v73
	v_pk_add_f32 v[10:11], v[10:11], v[12:13]
	v_pk_add_f32 v[12:13], v[66:67], v[68:69]
	v_pk_add_f32 v[66:67], v[86:87], v[88:89]
	v_pk_add_f32 v[10:11], v[10:11], v[12:13]
	v_pk_add_f32 v[12:13], v[66:67], v[66:67] op_sel:[0,1] op_sel_hi:[1,0]
	v_add_f32_e32 v10, 0, v10
	v_add_f32_e32 v98, v22, v23
	v_mov_b32_e32 v101, v20
	v_mov_b32_e32 v99, v19
	v_mov_b32_e32 v13, v21
	v_add_f32_e32 v100, v10, v11
	v_pk_add_f32 v[68:69], v[90:91], v[98:99]
	v_pk_add_f32 v[10:11], v[100:101], v[12:13]
	v_pk_add_f32 v[86:87], v[102:103], v[104:105]
	v_pk_add_f32 v[10:11], v[10:11], v[68:69]
	v_pk_add_f32 v[66:67], v[86:87], v[86:87] op_sel:[0,1] op_sel_hi:[1,0]
	v_pk_add_f32 v[10:11], v[10:11], v[10:11] op_sel:[0,1] op_sel_hi:[1,0]
	v_add_f32_e32 v106, v8, v9
	v_mov_b32_e32 v67, v3
	v_mov_b32_e32 v11, v2
	v_pk_add_f32 v[88:89], v[106:107], v[108:109]
	v_pk_add_f32 v[10:11], v[10:11], v[66:67]
	v_pk_mul_f32 v[12:13], v[62:63], v[70:71] op_sel_hi:[1,0]
	v_pk_add_f32 v[10:11], v[10:11], v[88:89]
	s_waitcnt vmcnt(2)
	v_pk_fma_f32 v[12:13], v[28:29], v[12:13], v[32:33]
	v_add_f32_e32 v10, v10, v11
	ds_bpermute_b32 v11, v1, v10
	v_bfe_u32 v28, v12, 16, 1
	v_bfe_u32 v29, v13, 16, 1
	v_add3_u32 v12, v12, v28, s19
	v_add3_u32 v13, v13, v29, s19
	s_waitcnt lgkmcnt(0)
	v_add_f32_e32 v10, v10, v11
	ds_bpermute_b32 v11, v71, v10
	v_lshrrev_b32_e32 v12, 16, v12
	s_waitcnt lgkmcnt(0)
	v_add_f32_e32 v10, v10, v11
	ds_bpermute_b32 v11, v92, v10
	s_waitcnt lgkmcnt(0)
	v_add_f32_e32 v10, v10, v11
	ds_bpermute_b32 v11, v93, v10
	s_waitcnt lgkmcnt(0)
	v_add_f32_e32 v10, v10, v11
	ds_bpermute_b32 v11, v94, v10
	s_waitcnt lgkmcnt(0)
	v_add_f32_e32 v66, v10, v11
	v_pk_mul_f32 v[10:11], v[64:65], v[70:71] op_sel_hi:[1,0]
	ds_bpermute_b32 v67, v95, v66
	v_pk_fma_f32 v[10:11], v[26:27], v[10:11], v[30:31]
	s_waitcnt lgkmcnt(0)
	v_add_f32_e32 v30, v66, v67
	v_bfe_u32 v26, v10, 16, 1
	v_bfe_u32 v27, v11, 16, 1
	v_add3_u32 v10, v10, v26, s19
	v_add3_u32 v11, v11, v27, s19
	v_lshrrev_b32_e32 v10, 16, v10
	v_and_or_b32 v10, v11, s17, v10
	v_and_or_b32 v11, v13, s17, v12
	global_store_dwordx2 v[76:77], v[10:11], off offset:-512 nt
	v_mov_b32_e32 v10, v216
	v_mov_b32_e32 v11, v217
	v_mov_b32_e32 v12, v218
	v_mov_b32_e32 v13, v219
	s_nop 0
	v_mov_b32_e32 v26, v220
	v_mov_b32_e32 v27, v221
	v_mov_b32_e32 v28, v222
	v_mov_b32_e32 v29, v223
	v_fmamk_f32 v83, v30, 0xba000000, v83
	v_fmamk_f32 v85, v30, 0xba000000, v85
	v_fmamk_f32 v79, v30, 0xba000000, v79
	v_fmamk_f32 v81, v30, 0xba000000, v81
	v_fmac_f32_e32 v82, 0xba000000, v30
	v_fmac_f32_e32 v84, 0xba000000, v30
	v_fmac_f32_e32 v78, 0xba000000, v30
	v_fmac_f32_e32 v80, 0xba000000, v30
	v_fmamk_f32 v75, v30, 0xba000000, v75
	v_fmac_f32_e32 v74, 0xba000000, v30
	v_fmamk_f32 v73, v30, 0xba000000, v73
	v_fmac_f32_e32 v72, 0xba000000, v30
	v_mov_b32_e32 v32, v85
	v_mov_b32_e32 v33, v81
	v_mov_b32_e32 v64, v83
	v_mov_b32_e32 v65, v79
	v_fmamk_f32 v25, v30, 0xba000000, v25
	v_fmac_f32_e32 v24, 0xba000000, v30
	v_fmamk_f32 v23, v30, 0xba000000, v23
	v_fmac_f32_e32 v22, 0xba000000, v30
	v_fmamk_f32 v19, v30, 0xba000000, v19
	v_fmac_f32_e32 v18, 0xba000000, v30
	v_fmamk_f32 v21, v30, 0xba000000, v21
	v_fmac_f32_e32 v20, 0xba000000, v30
	v_fmamk_f32 v17, v30, 0xba000000, v17
	v_fmac_f32_e32 v16, 0xba000000, v30
	v_fmamk_f32 v15, v30, 0xba000000, v15
	v_fmac_f32_e32 v14, 0xba000000, v30
	v_fmamk_f32 v9, v30, 0xba000000, v9
	v_fmac_f32_e32 v8, 0xba000000, v30
	v_fmamk_f32 v7, v30, 0xba000000, v7
	v_fmac_f32_e32 v6, 0xba000000, v30
	v_fmamk_f32 v5, v30, 0xba000000, v5
	v_fmac_f32_e32 v4, 0xba000000, v30
	v_fmamk_f32 v3, v30, 0xba000000, v3
	v_fmac_f32_e32 v2, 0xba000000, v30
	v_mov_b32_e32 v30, v84
	v_mov_b32_e32 v31, v80
	v_mov_b32_e32 v62, v82
	v_mov_b32_e32 v63, v78
	v_pk_mul_f32 v[66:67], v[72:73], v[72:73]
	v_pk_mul_f32 v[68:69], v[74:75], v[74:75]
	v_pk_mul_f32 v[32:33], v[32:33], v[32:33]
	v_pk_mul_f32 v[64:65], v[64:65], v[64:65]
	v_pk_mov_b32 v[102:103], v[68:69], v[66:67] op_sel:[1,0]
	v_mov_b32_e32 v69, v67
	v_pk_fma_f32 v[30:31], v[30:31], v[30:31], v[32:33]
	v_pk_fma_f32 v[32:33], v[62:63], v[62:63], v[64:65]
	v_pk_add_f32 v[62:63], v[102:103], v[68:69]
	v_pk_add_f32 v[30:31], v[30:31], v[32:33]
	v_pk_add_f32 v[32:33], v[62:63], v[62:63] op_sel_hi:[0,1]
	v_pk_add_f32 v[30:31], v[30:31], v[30:31] op_sel_hi:[0,1]
	v_mul_f32_e32 v32, v18, v18
	v_mul_f32_e32 v30, v19, v19
	v_pk_add_f32 v[68:69], v[32:33], v[30:31]
	v_pk_mul_f32 v[30:31], v[60:61], v[70:71] op_sel_hi:[1,0]
	v_pk_mul_f32 v[32:33], v[58:59], v[70:71] op_sel_hi:[1,0]
	v_mul_f32_e32 v76, v24, v24
	v_mul_f32_e32 v86, v22, v22
	v_pk_fma_f32 v[66:67], v[24:25], v[24:25], v[76:77] op_sel_hi:[1,1,0]
	v_pk_fma_f32 v[76:77], v[22:23], v[22:23], v[86:87] op_sel_hi:[1,1,0]
	v_pk_mul_f32 v[88:89], v[14:15], v[14:15]
	v_pk_mul_f32 v[90:91], v[16:17], v[16:17]
	v_mul_f32_e32 v66, v20, v20
	v_mul_f32_e32 v76, v21, v21
	v_pk_mov_b32 v[86:87], v[90:91], v[88:89] op_sel:[1,0]
	v_mov_b32_e32 v91, v89
	v_pk_add_f32 v[62:63], v[66:67], v[76:77]
	v_mul_f32_e32 v98, v8, v8
	v_mul_f32_e32 v100, v6, v6
	v_pk_add_f32 v[64:65], v[86:87], v[90:91]
	v_pk_fma_f32 v[88:89], v[8:9], v[8:9], v[98:99] op_sel_hi:[1,1,0]
	v_pk_fma_f32 v[98:99], v[6:7], v[6:7], v[100:101] op_sel_hi:[1,1,0]
	v_pk_add_f32 v[64:65], v[64:65], v[64:65] op_sel_hi:[0,1]
	v_mul_f32_e32 v88, v2, v2
	v_mul_f32_e32 v98, v3, v3
	v_mul_f32_e32 v64, v4, v4
	v_pk_add_f32 v[66:67], v[88:89], v[98:99]
	s_waitcnt vmcnt(3)
	v_pk_fma_f32 v[12:13], v[12:13], v[32:33], v[28:29]
	v_pk_fma_f32 v[10:11], v[10:11], v[30:31], v[26:27]
	v_bfe_u32 v28, v12, 16, 1
	v_bfe_u32 v26, v10, 16, 1
	v_bfe_u32 v27, v11, 16, 1
	v_bfe_u32 v29, v13, 16, 1
	v_add3_u32 v10, v10, v26, s19
	v_add3_u32 v12, v12, v28, s19
	v_add3_u32 v11, v11, v27, s19
	v_add3_u32 v13, v13, v29, s19
	v_lshrrev_b32_e32 v10, 16, v10
	v_lshrrev_b32_e32 v12, 16, v12
	v_and_or_b32 v10, v11, s17, v10
	v_and_or_b32 v11, v13, s17, v12
	global_store_dwordx2 v[54:55], v[10:11], off offset:-4096 nt
	v_mov_b32_e32 v26, v160
	v_mov_b32_e32 v27, v161
	v_mov_b32_e32 v28, v162
	v_mov_b32_e32 v29, v163
	v_mov_b32_e32 v30, v164
	v_mov_b32_e32 v31, v165
	v_mov_b32_e32 v32, v166
	v_mov_b32_e32 v33, v167
	v_pk_add_f32 v[10:11], v[62:63], v[68:69]
	s_nop 0
	v_pk_add_f32 v[10:11], v[10:11], v[10:11] op_sel_hi:[0,1]
	v_mul_f32_e32 v10, v5, v5
	v_pk_add_f32 v[10:11], v[64:65], v[10:11]
	s_nop 0
	v_pk_add_f32 v[10:11], v[66:67], v[10:11]
	s_nop 0
	v_add_f32_e32 v10, v10, v11
	ds_bpermute_b32 v11, v1, v10
	s_waitcnt lgkmcnt(0)
	v_add_f32_e32 v10, v10, v11
	ds_bpermute_b32 v11, v71, v10
	s_waitcnt lgkmcnt(0)
	v_add_f32_e32 v10, v10, v11
	ds_bpermute_b32 v11, v92, v10
	s_waitcnt lgkmcnt(0)
	v_add_f32_e32 v10, v10, v11
	ds_bpermute_b32 v11, v93, v10
	s_waitcnt lgkmcnt(0)
	v_add_f32_e32 v10, v10, v11
	ds_bpermute_b32 v11, v94, v10
	s_waitcnt lgkmcnt(0)
	v_add_f32_e32 v10, v10, v11
	ds_bpermute_b32 v11, v95, v10
	s_waitcnt lgkmcnt(0)
	v_add_f32_e32 v10, v10, v11
	v_fmamk_f32 v10, v10, 0x3a000000, v96
	v_mul_f32_e32 v11, 0x4f800000, v10
	v_cmp_gt_f32_e32 vcc, s18, v10
	s_nop 1
	v_cndmask_b32_e32 v10, v10, v11, vcc
	v_sqrt_f32_e32 v11, v10
	s_nop 0
	v_add_u32_e32 v12, -1, v11
	v_add_u32_e32 v13, 1, v11
	v_fma_f32 v58, -v12, v11, v10
	v_fma_f32 v59, -v13, v11, v10
	v_cmp_ge_f32_e64 s[0:1], 0, v58
	s_nop 1
	v_cndmask_b32_e64 v11, v11, v12, s[0:1]
	v_cmp_lt_f32_e64 s[0:1], 0, v59
	s_nop 1
	v_cndmask_b32_e64 v11, v11, v13, s[0:1]
	v_mul_f32_e32 v12, 0x37800000, v11
	v_cndmask_b32_e32 v11, v11, v12, vcc
	v_cmp_class_f32_e32 vcc, v10, v97
	s_nop 1
	v_cndmask_b32_e32 v10, v11, v10, vcc
	v_div_scale_f32 v11, s[0:1], v10, v10, 1.0
	v_rcp_f32_e32 v12, v11
	v_div_scale_f32 v13, vcc, 1.0, v10, 1.0
	v_fma_f32 v58, -v11, v12, 1.0
	v_fmac_f32_e32 v12, v58, v12
	v_mul_f32_e32 v58, v13, v12
	v_fma_f32 v59, -v11, v58, v13
	v_fmac_f32_e32 v58, v59, v12
	v_fma_f32 v11, -v11, v58, v13
	v_div_fmas_f32 v11, v11, v12, v58
	v_div_fixup_f32 v10, v11, v10, 1.0
	v_pk_mul_f32 v[12:13], v[84:85], v[10:11] op_sel_hi:[1,0]
	v_pk_mul_f32 v[58:59], v[82:83], v[10:11] op_sel_hi:[1,0]
	s_waitcnt vmcnt(4)
	v_pk_fma_f32 v[12:13], v[26:27], v[12:13], v[30:31]
	v_pk_fma_f32 v[28:29], v[28:29], v[58:59], v[32:33]
	v_bfe_u32 v11, v12, 16, 1
	v_bfe_u32 v26, v13, 16, 1
	v_bfe_u32 v27, v28, 16, 1
	v_bfe_u32 v30, v29, 16, 1
	v_add3_u32 v11, v12, v11, s19
	v_add3_u32 v12, v13, v26, s19
	v_add3_u32 v13, v28, v27, s19
	v_add3_u32 v26, v29, v30, s19
	v_lshrrev_b32_e32 v11, 16, v11
	v_lshrrev_b32_e32 v13, 16, v13
	v_and_or_b32 v12, v12, s17, v11
	v_and_or_b32 v13, v26, s17, v13
	global_store_dwordx2 v[54:55], v[12:13], off offset:-3584 nt
	v_mov_b32_e32 v26, v168
	v_mov_b32_e32 v27, v169
	v_mov_b32_e32 v28, v170
	v_mov_b32_e32 v29, v171
	v_mov_b32_e32 v30, v172
	v_mov_b32_e32 v31, v173
	v_mov_b32_e32 v32, v174
	v_mov_b32_e32 v33, v175
	v_pk_mul_f32 v[12:13], v[80:81], v[10:11] op_sel_hi:[1,0]
	v_pk_mul_f32 v[58:59], v[78:79], v[10:11] op_sel_hi:[1,0]
	s_waitcnt vmcnt(5)
	v_pk_fma_f32 v[12:13], v[26:27], v[12:13], v[30:31]
	v_pk_fma_f32 v[28:29], v[28:29], v[58:59], v[32:33]
	v_bfe_u32 v11, v12, 16, 1
	v_bfe_u32 v26, v13, 16, 1
	v_bfe_u32 v27, v28, 16, 1
	v_bfe_u32 v30, v29, 16, 1
	v_add3_u32 v11, v12, v11, s19
	v_add3_u32 v12, v13, v26, s19
	v_add3_u32 v13, v28, v27, s19
	v_add3_u32 v26, v29, v30, s19
	v_lshrrev_b32_e32 v11, 16, v11
	v_lshrrev_b32_e32 v13, 16, v13
	v_and_or_b32 v12, v12, s17, v11
	v_and_or_b32 v13, v26, s17, v13
	global_store_dwordx2 v[54:55], v[12:13], off offset:-3072 nt
	v_mov_b32_e32 v26, v176
	v_mov_b32_e32 v27, v177
	v_mov_b32_e32 v28, v178
	v_mov_b32_e32 v29, v179
	v_mov_b32_e32 v30, v180
	v_mov_b32_e32 v31, v181
	v_mov_b32_e32 v32, v182
	v_mov_b32_e32 v33, v183
	v_pk_mul_f32 v[12:13], v[74:75], v[10:11] op_sel_hi:[1,0]
	v_pk_mul_f32 v[58:59], v[72:73], v[10:11] op_sel_hi:[1,0]
	s_waitcnt vmcnt(6)
	v_pk_fma_f32 v[12:13], v[26:27], v[12:13], v[30:31]
	v_pk_fma_f32 v[28:29], v[28:29], v[58:59], v[32:33]
	v_bfe_u32 v11, v12, 16, 1
	v_bfe_u32 v26, v13, 16, 1
	v_bfe_u32 v27, v28, 16, 1
	v_bfe_u32 v30, v29, 16, 1
	v_add3_u32 v11, v12, v11, s19
	v_add3_u32 v12, v13, v26, s19
	v_add3_u32 v13, v28, v27, s19
	v_add3_u32 v26, v29, v30, s19
	v_lshrrev_b32_e32 v11, 16, v11
	v_lshrrev_b32_e32 v13, 16, v13
	v_and_or_b32 v12, v12, s17, v11
	v_and_or_b32 v13, v26, s17, v13
	global_store_dwordx2 v[54:55], v[12:13], off offset:-2560 nt
	v_mov_b32_e32 v26, v184
	v_mov_b32_e32 v27, v185
	v_mov_b32_e32 v28, v186
	v_mov_b32_e32 v29, v187
	v_mov_b32_e32 v30, v188
	v_mov_b32_e32 v31, v189
	v_mov_b32_e32 v32, v190
	v_mov_b32_e32 v33, v191
	v_pk_mul_f32 v[12:13], v[24:25], v[10:11] op_sel_hi:[1,0]
	v_pk_mul_f32 v[22:23], v[22:23], v[10:11] op_sel_hi:[1,0]
	s_waitcnt vmcnt(7)
	v_pk_fma_f32 v[12:13], v[26:27], v[12:13], v[30:31]
	v_pk_fma_f32 v[22:23], v[28:29], v[22:23], v[32:33]
	v_bfe_u32 v11, v12, 16, 1
	v_bfe_u32 v24, v13, 16, 1
	v_bfe_u32 v25, v22, 16, 1
	v_bfe_u32 v26, v23, 16, 1
	v_add3_u32 v11, v12, v11, s19
	v_add3_u32 v12, v13, v24, s19
	v_add3_u32 v13, v22, v25, s19
	v_add3_u32 v22, v23, v26, s19
	v_lshrrev_b32_e32 v11, 16, v11
	v_lshrrev_b32_e32 v13, 16, v13
	v_and_or_b32 v12, v12, s17, v11
	v_and_or_b32 v13, v22, s17, v13
	global_store_dwordx2 v[54:55], v[12:13], off offset:-2048 nt
	v_mov_b32_e32 v22, v192
	v_mov_b32_e32 v23, v193
	v_mov_b32_e32 v24, v194
	v_mov_b32_e32 v25, v195
	v_mov_b32_e32 v26, v196
	v_mov_b32_e32 v27, v197
	v_mov_b32_e32 v28, v198
	v_mov_b32_e32 v29, v199
	v_pk_mul_f32 v[12:13], v[20:21], v[10:11] op_sel_hi:[1,0]
	v_pk_mul_f32 v[18:19], v[18:19], v[10:11] op_sel_hi:[1,0]
	s_waitcnt vmcnt(8)
	v_pk_fma_f32 v[12:13], v[22:23], v[12:13], v[26:27]
	v_pk_fma_f32 v[18:19], v[24:25], v[18:19], v[28:29]
	v_bfe_u32 v11, v12, 16, 1
	v_bfe_u32 v20, v13, 16, 1
	v_bfe_u32 v21, v18, 16, 1
	v_bfe_u32 v22, v19, 16, 1
	v_add3_u32 v11, v12, v11, s19
	v_add3_u32 v12, v13, v20, s19
	v_add3_u32 v13, v18, v21, s19
	v_add3_u32 v18, v19, v22, s19
	v_lshrrev_b32_e32 v11, 16, v11
	v_lshrrev_b32_e32 v13, 16, v13
	v_and_or_b32 v12, v12, s17, v11
	v_and_or_b32 v13, v18, s17, v13
	global_store_dwordx2 v[54:55], v[12:13], off offset:-1536 nt
	v_mov_b32_e32 v18, v200
	v_mov_b32_e32 v19, v201
	v_mov_b32_e32 v20, v202
	v_mov_b32_e32 v21, v203
	v_mov_b32_e32 v22, v204
	v_mov_b32_e32 v23, v205
	v_mov_b32_e32 v24, v206
	v_mov_b32_e32 v25, v207
	v_pk_mul_f32 v[12:13], v[16:17], v[10:11] op_sel_hi:[1,0]
	v_pk_mul_f32 v[14:15], v[14:15], v[10:11] op_sel_hi:[1,0]
	s_waitcnt vmcnt(9)
	v_pk_fma_f32 v[12:13], v[18:19], v[12:13], v[22:23]
	v_pk_fma_f32 v[14:15], v[20:21], v[14:15], v[24:25]
	v_bfe_u32 v11, v12, 16, 1
	v_bfe_u32 v16, v13, 16, 1
	v_bfe_u32 v17, v14, 16, 1
	v_bfe_u32 v18, v15, 16, 1
	v_add3_u32 v11, v12, v11, s19
	v_add3_u32 v12, v13, v16, s19
	v_add3_u32 v13, v14, v17, s19
	v_add3_u32 v14, v15, v18, s19
	v_lshrrev_b32_e32 v11, 16, v11
	v_lshrrev_b32_e32 v13, 16, v13
	v_and_or_b32 v12, v12, s17, v11
	v_and_or_b32 v13, v14, s17, v13
	global_store_dwordx2 v[54:55], v[12:13], off offset:-1024 nt
	v_mov_b32_e32 v12, v208
	v_mov_b32_e32 v13, v209
	v_mov_b32_e32 v14, v210
	v_mov_b32_e32 v15, v211
	s_nop 0
	v_mov_b32_e32 v16, v212
	v_mov_b32_e32 v17, v213
	v_mov_b32_e32 v18, v214
	v_mov_b32_e32 v19, v215
	v_pk_mul_f32 v[8:9], v[8:9], v[10:11] op_sel_hi:[1,0]
	v_pk_mul_f32 v[6:7], v[6:7], v[10:11] op_sel_hi:[1,0]
	s_waitcnt vmcnt(10)
	v_pk_fma_f32 v[8:9], v[12:13], v[8:9], v[16:17]
	v_pk_fma_f32 v[6:7], v[14:15], v[6:7], v[18:19]
	v_bfe_u32 v11, v8, 16, 1
	v_bfe_u32 v13, v6, 16, 1
	v_bfe_u32 v12, v9, 16, 1
	v_bfe_u32 v14, v7, 16, 1
	v_add3_u32 v8, v8, v11, s19
	v_add3_u32 v6, v6, v13, s19
	v_add3_u32 v9, v9, v12, s19
	v_add3_u32 v7, v7, v14, s19
	v_lshrrev_b32_e32 v8, 16, v8
	v_lshrrev_b32_e32 v11, 16, v6
	v_and_or_b32 v6, v9, s17, v8
	v_and_or_b32 v7, v7, s17, v11
	global_store_dwordx2 v[54:55], v[6:7], off offset:-512 nt
	v_mov_b32_e32 v6, v216
	v_mov_b32_e32 v7, v217
	v_mov_b32_e32 v8, v218
	v_mov_b32_e32 v9, v219
	s_nop 0
	v_mov_b32_e32 v12, v220
	v_mov_b32_e32 v13, v221
	v_mov_b32_e32 v14, v222
	v_mov_b32_e32 v15, v223
	v_pk_mul_f32 v[2:3], v[2:3], v[10:11] op_sel_hi:[1,0]
	v_pk_mul_f32 v[4:5], v[4:5], v[10:11] op_sel_hi:[1,0]
	s_waitcnt vmcnt(11)
	v_pk_fma_f32 v[2:3], v[6:7], v[2:3], v[12:13]
	v_pk_fma_f32 v[4:5], v[8:9], v[4:5], v[14:15]
	v_bfe_u32 v6, v2, 16, 1
	v_bfe_u32 v8, v4, 16, 1
	v_bfe_u32 v7, v3, 16, 1
	v_bfe_u32 v9, v5, 16, 1
	v_add3_u32 v2, v2, v6, s19
	v_add3_u32 v4, v4, v8, s19
	v_add3_u32 v3, v3, v7, s19
	v_add3_u32 v5, v5, v9, s19
	v_lshrrev_b32_e32 v2, 16, v2
	v_lshrrev_b32_e32 v4, 16, v4
	v_and_or_b32 v2, v3, s17, v2
	v_and_or_b32 v3, v5, s17, v4
	global_store_dwordx2 v[54:55], v[2:3], off nt
	v_lshl_add_u64 v[54:55], v[54:55], 0, s[12:13]
	s_cbranch_scc1 .LBB0_980

.LBB0_1279:
	s_cmp_lt_i32 s84, 12
	s_cselect_b64 s[2:3], -1, 0
	s_and_b64 s[0:1], s[2:3], s[0:1]
	s_cmpk_lt_i32 s72, 0x4000
	s_cselect_b64 s[2:3], -1, 0
	s_and_b64 s[0:1], s[0:1], s[2:3]
	s_andn2_b64 vcc, exec, s[0:1]
	s_cbranch_vccnz .LBB0_1286
	v_mbcnt_hi_u32_b32 v0, -1, v148
	v_and_b32_e32 v1, 64, v0
	v_add_u32_e32 v1, 64, v1
	v_xor_b32_e32 v2, 1, v0
	v_cmp_lt_i32_e32 vcc, v2, v1
	s_lshl_b32 s4, s72, 1
	s_cmp_lg_u64 s[70:71], 0
	v_cndmask_b32_e32 v2, v0, v2, vcc
	v_lshlrev_b32_e32 v88, 2, v2
	v_xor_b32_e32 v2, 2, v0
	v_cmp_lt_i32_e32 vcc, v2, v1
	s_cselect_b64 s[0:1], -1, 0
	s_ashr_i32 s5, s4, 31
	v_cndmask_b32_e32 v2, v0, v2, vcc
	v_lshlrev_b32_e32 v89, 2, v2
	v_xor_b32_e32 v2, 4, v0
	v_cmp_lt_i32_e32 vcc, v2, v1
	s_lshl_b32 s6, s33, 4
	s_lshl_b64 s[2:3], s[4:5], 13
	v_cndmask_b32_e32 v2, v0, v2, vcc
	v_lshlrev_b32_e32 v90, 2, v2
	v_xor_b32_e32 v2, 8, v0
	v_cmp_lt_i32_e32 vcc, v2, v1
	s_add_u32 s2, s70, s2
	v_lshlrev_b32_e32 v22, 4, v152
	v_cndmask_b32_e32 v2, v0, v2, vcc
	v_lshlrev_b32_e32 v91, 2, v2
	v_xor_b32_e32 v2, 16, v0
	v_cmp_lt_i32_e32 vcc, v2, v1
	v_mov_b32_e32 v23, 0
	v_readlane_b32 s8, v239, 0
	v_cndmask_b32_e32 v2, v0, v2, vcc
	s_addc_u32 s3, s71, s3
	v_lshlrev_b32_e32 v92, 2, v2
	v_xor_b32_e32 v2, 32, v0
	v_readlane_b32 s9, v239, 1
	v_lshl_add_u64 v[20:21], s[2:3], 0, v[22:23]
	s_mov_b64 s[2:3], 0x2000
	s_ashr_i32 s7, s6, 31
	v_cmp_lt_i32_e32 vcc, v2, v1
	v_readlane_b32 s10, v239, 2
	v_readlane_b32 s11, v239, 3
	v_readlane_b32 s14, v239, 6
	v_readlane_b32 s15, v239, 7
	v_lshl_add_u64 v[20:21], v[20:21], 0, s[2:3]
	s_lshl_b64 s[8:9], s[6:7], 13
	s_lshl_b64 s[2:3], s[4:5], 12
	v_cndmask_b32_e32 v0, v0, v2, vcc
	s_mov_b64 s[10:11], s[14:15]
	s_add_u32 s2, s78, s2
	v_lshlrev_b32_e32 v93, 2, v0
	v_lshl_add_u64 v[0:1], s[10:11], 0, v[22:23]
	v_lshl_add_u64 v[2:3], s[68:69], 0, v[22:23]
	v_or_b32_e32 v6, 0x1000, v22
	v_or_b32_e32 v10, 0x1400, v22
	v_or_b32_e32 v14, 0x1800, v22
	v_or_b32_e32 v18, 0x1c00, v22
	v_lshlrev_b32_e32 v22, 3, v152
	s_addc_u32 s3, s79, s3
	v_readlane_b32 s12, v239, 4
	v_readlane_b32 s13, v239, 5
	v_mov_b32_e32 v7, v23
	v_mov_b32_e32 v11, v23
	v_mov_b32_e32 v15, v23
	v_mov_b32_e32 v19, v23
	v_lshl_add_u64 v[22:23], s[2:3], 0, v[22:23]
	s_mov_b64 s[2:3], 0x38001e00
	v_cndmask_b32_e64 v24, 0, 1, s[0:1]
	s_movk_i32 s13, 0x1000
	v_lshl_add_u64 v[4:5], s[10:11], 0, v[6:7]
	v_lshl_add_u64 v[6:7], s[68:69], 0, v[6:7]
	v_lshl_add_u64 v[8:9], s[10:11], 0, v[10:11]
	v_lshl_add_u64 v[10:11], s[68:69], 0, v[10:11]
	v_lshl_add_u64 v[12:13], s[10:11], 0, v[14:15]
	v_lshl_add_u64 v[14:15], s[68:69], 0, v[14:15]
	v_lshl_add_u64 v[16:17], s[10:11], 0, v[18:19]
	v_lshl_add_u64 v[18:19], s[68:69], 0, v[18:19]
	v_lshl_add_u64 v[22:23], v[22:23], 0, s[2:3]
	s_lshl_b64 s[10:11], s[6:7], 12
	s_movk_i32 s5, 0xf000
	s_brev_b32 s7, 31
	s_mov_b32 s12, 0x3f9837f0
	v_cmp_ne_u32_e64 s[0:1], 1, v24
	v_mov_b32_e32 v94, 0x3727c5ac
	s_mov_b32 s14, 0xf800000
	v_mov_b32_e32 v95, 0x260
	s_movk_i32 s15, 0xe000
	global_load_dwordx4 v[160:163], v[0:1], off
	global_load_dwordx4 v[164:167], v[2:3], off
	global_load_dwordx4 v[168:171], v[0:1], off offset:1024
	global_load_dwordx4 v[172:175], v[2:3], off offset:1024
	global_load_dwordx4 v[176:179], v[0:1], off offset:2048
	global_load_dwordx4 v[180:183], v[2:3], off offset:2048
	global_load_dwordx4 v[184:187], v[0:1], off offset:3072
	global_load_dwordx4 v[188:191], v[2:3], off offset:3072
	global_load_dwordx4 v[192:195], v[4:5], off
	global_load_dwordx4 v[196:199], v[6:7], off
	global_load_dwordx4 v[200:203], v[8:9], off
	global_load_dwordx4 v[204:207], v[10:11], off
	global_load_dwordx4 v[208:211], v[12:13], off
	global_load_dwordx4 v[212:215], v[14:15], off
	global_load_dwordx4 v[216:219], v[16:17], off
	global_load_dwordx4 v[220:223], v[18:19], off
	s_waitcnt vmcnt(0)
	s_branch .LBB0_1282

.LBB0_1282:
	v_add_co_u32_e32 v30, vcc, 0xfffff000, v22
	s_nop 1
	v_addc_co_u32_e32 v31, vcc, -1, v23, vcc
	global_load_dwordx2 v[32:33], v[30:31], off offset:-3584 nt
	global_load_dwordx2 v[34:35], v[30:31], off offset:-3072 nt
	global_load_dwordx2 v[36:37], v[30:31], off offset:-2560 nt
	v_add_co_u32_e32 v38, vcc, 0xf7fff000, v22
	global_load_dwordx2 v[40:41], v[30:31], off offset:-2048 nt
	s_nop 0
	v_addc_co_u32_e32 v39, vcc, -1, v23, vcc
	global_load_dwordx2 v[42:43], v[38:39], off offset:-3584 nt
	global_load_dwordx2 v[44:45], v[38:39], off offset:-3072 nt
	global_load_dwordx2 v[46:47], v[38:39], off offset:-2560 nt
	global_load_dwordx2 v[48:49], v[38:39], off offset:-2048 nt
	global_load_dwordx2 v[50:51], v[38:39], off offset:-1536 nt
	global_load_dwordx2 v[58:59], v[30:31], off offset:-1536 nt
	v_add_co_u32_e32 v28, vcc, s7, v22
	s_waitcnt vmcnt(0)
	v_lshlrev_b32_e32 v52, 16, v36
	v_addc_co_u32_e32 v29, vcc, -1, v23, vcc
	global_load_dwordx2 v[66:67], v[22:23], off offset:-4096 nt
	global_load_dwordx2 v[24:25], v[28:29], off nt
	global_load_dwordx2 v[68:69], v[30:31], off offset:-1024 nt
	global_load_dwordx2 v[70:71], v[30:31], off offset:-512 nt
	global_load_dwordx2 v[72:73], v[38:39], off offset:-1024 nt
	global_load_dwordx2 v[74:75], v[38:39], off offset:-512 nt
	global_load_dwordx2 v[76:77], v[38:39], off nt
	global_load_dwordx2 v[26:27], v[28:29], off offset:-3584 nt
	v_lshlrev_b32_e32 v30, 16, v32
	v_and_b32_e32 v31, 0xffff0000, v32
	v_lshlrev_b32_e32 v32, 16, v33
	v_and_b32_e32 v33, 0xffff0000, v33
	v_lshlrev_b32_e32 v38, 16, v34
	v_and_b32_e32 v39, 0xffff0000, v34
	v_lshlrev_b32_e32 v34, 16, v35
	v_and_b32_e32 v35, 0xffff0000, v35
	v_lshlrev_b32_e32 v54, 16, v42
	v_and_b32_e32 v55, 0xffff0000, v42
	v_lshlrev_b32_e32 v42, 16, v43
	v_and_b32_e32 v43, 0xffff0000, v43
	v_lshlrev_b32_e32 v56, 16, v44
	s_waitcnt lgkmcnt(0)
	v_and_b32_e32 v57, 0xffff0000, v44
	v_lshlrev_b32_e32 v44, 16, v45
	v_and_b32_e32 v45, 0xffff0000, v45
	v_and_b32_e32 v53, 0xffff0000, v36
	v_lshlrev_b32_e32 v36, 16, v37
	v_and_b32_e32 v37, 0xffff0000, v37
	v_lshlrev_b32_e32 v78, 16, v46
	v_and_b32_e32 v79, 0xffff0000, v46
	v_lshlrev_b32_e32 v46, 16, v47
	v_and_b32_e32 v47, 0xffff0000, v47
	v_pk_fma_f32 v[84:85], v[42:43], s[12:13], v[32:33] op_sel_hi:[1,0,1]
	v_pk_fma_f32 v[86:87], v[54:55], s[12:13], v[30:31] op_sel_hi:[1,0,1]
	v_pk_fma_f32 v[62:63], v[44:45], s[12:13], v[34:35] op_sel_hi:[1,0,1]
	v_pk_fma_f32 v[64:65], v[56:57], s[12:13], v[38:39] op_sel_hi:[1,0,1]
	v_lshlrev_b32_e32 v60, 16, v40
	v_and_b32_e32 v61, 0xffff0000, v40
	v_lshlrev_b32_e32 v40, 16, v41
	v_and_b32_e32 v41, 0xffff0000, v41
	v_lshlrev_b32_e32 v80, 16, v48
	v_and_b32_e32 v81, 0xffff0000, v48
	v_lshlrev_b32_e32 v48, 16, v49
	v_and_b32_e32 v49, 0xffff0000, v49
	v_pk_fma_f32 v[54:55], v[46:47], s[12:13], v[36:37] op_sel_hi:[1,0,1]
	v_pk_fma_f32 v[56:57], v[78:79], s[12:13], v[52:53] op_sel_hi:[1,0,1]
	v_mov_b32_e32 v30, v86
	v_mov_b32_e32 v31, v64
	v_mov_b32_e32 v32, v87
	v_mov_b32_e32 v33, v65
	v_mov_b32_e32 v34, v84
	v_mov_b32_e32 v35, v62
	v_mov_b32_e32 v36, v85
	v_mov_b32_e32 v37, v63
	v_pk_fma_f32 v[48:49], v[48:49], s[12:13], v[40:41] op_sel_hi:[1,0,1]
	v_pk_mov_b32 v[38:39], v[56:57], v[54:55] op_sel:[1,0]
	v_mov_b32_e32 v40, v56
	v_mov_b32_e32 v41, v55
	v_pk_add_f32 v[30:31], v[30:31], v[32:33]
	v_pk_add_f32 v[32:33], v[34:35], v[36:37]
	v_pk_add_f32 v[34:35], v[38:39], v[40:41]
	v_pk_add_f32 v[30:31], v[30:31], v[32:33]
	v_lshlrev_b32_e32 v38, 16, v50
	v_and_b32_e32 v39, 0xffff0000, v50
	v_lshlrev_b32_e32 v40, 16, v51
	v_and_b32_e32 v41, 0xffff0000, v51
	v_lshlrev_b32_e32 v42, 16, v58
	v_and_b32_e32 v43, 0xffff0000, v58
	v_lshlrev_b32_e32 v44, 16, v59
	v_and_b32_e32 v45, 0xffff0000, v59
	v_pk_fma_f32 v[52:53], v[80:81], s[12:13], v[60:61] op_sel_hi:[1,0,1]
	v_pk_add_f32 v[32:33], v[34:35], v[34:35] op_sel:[0,1] op_sel_hi:[1,0]
	v_add_f32_e32 v30, 0, v30
	v_pk_fma_f32 v[58:59], v[40:41], s[12:13], v[44:45] op_sel_hi:[1,0,1]
	v_pk_fma_f32 v[60:61], v[38:39], s[12:13], v[42:43] op_sel_hi:[1,0,1]
	v_add_f32_e32 v30, v30, v31
	v_add_f32_e32 v34, v52, v53
	v_add_f32_e32 v36, v48, v49
	v_mov_b32_e32 v31, v60
	v_mov_b32_e32 v33, v61
	v_mov_b32_e32 v35, v58
	v_mov_b32_e32 v37, v59
	v_pk_add_f32 v[30:31], v[30:31], v[32:33]
	v_pk_add_f32 v[32:33], v[34:35], v[36:37]
	s_waitcnt vmcnt(0)
	v_lshlrev_b32_e32 v36, 16, v68
	v_pk_add_f32 v[30:31], v[30:31], v[32:33]
	v_lshlrev_b32_e32 v32, 16, v72
	v_and_b32_e32 v33, 0xffff0000, v72
	v_lshlrev_b32_e32 v34, 16, v73
	v_and_b32_e32 v35, 0xffff0000, v73
	v_and_b32_e32 v37, 0xffff0000, v68
	v_lshlrev_b32_e32 v38, 16, v69
	v_and_b32_e32 v39, 0xffff0000, v69
	v_pk_fma_f32 v[68:69], v[34:35], s[12:13], v[38:39] op_sel_hi:[1,0,1]
	v_pk_fma_f32 v[72:73], v[32:33], s[12:13], v[36:37] op_sel_hi:[1,0,1]
	v_mov_b32_e32 v35, v69
	v_pk_mov_b32 v[32:33], v[72:73], v[68:69] op_sel:[1,0]
	v_mov_b32_e32 v34, v72
	v_pk_add_f32 v[32:33], v[32:33], v[34:35]
	v_lshlrev_b32_e32 v34, 16, v74
	v_and_b32_e32 v35, 0xffff0000, v74
	v_lshlrev_b32_e32 v36, 16, v75
	v_and_b32_e32 v37, 0xffff0000, v75
	v_lshlrev_b32_e32 v38, 16, v70
	v_and_b32_e32 v39, 0xffff0000, v70
	v_lshlrev_b32_e32 v40, 16, v71
	v_and_b32_e32 v41, 0xffff0000, v71
	v_pk_fma_f32 v[70:71], v[36:37], s[12:13], v[40:41] op_sel_hi:[1,0,1]
	v_pk_fma_f32 v[78:79], v[34:35], s[12:13], v[38:39] op_sel_hi:[1,0,1]
	v_lshlrev_b32_e32 v38, 16, v76
	v_and_b32_e32 v39, 0xffff0000, v76
	v_lshlrev_b32_e32 v40, 16, v77
	v_and_b32_e32 v41, 0xffff0000, v77
	v_lshlrev_b32_e32 v42, 16, v66
	v_and_b32_e32 v43, 0xffff0000, v66
	v_lshlrev_b32_e32 v44, 16, v67
	v_and_b32_e32 v45, 0xffff0000, v67
	v_pk_add_f32 v[30:31], v[30:31], v[30:31] op_sel:[0,1] op_sel_hi:[1,0]
	v_pk_add_f32 v[32:33], v[32:33], v[32:33] op_sel:[0,1] op_sel_hi:[1,0]
	v_pk_fma_f32 v[76:77], v[40:41], s[12:13], v[44:45] op_sel_hi:[1,0,1]
	v_pk_fma_f32 v[80:81], v[38:39], s[12:13], v[42:43] op_sel_hi:[1,0,1]
	v_add_f32_e32 v34, v78, v79
	v_add_f32_e32 v36, v70, v71
	v_mov_b32_e32 v31, v80
	v_mov_b32_e32 v33, v81
	v_mov_b32_e32 v35, v76
	v_mov_b32_e32 v37, v77
	v_pk_add_f32 v[30:31], v[30:31], v[32:33]
	v_pk_add_f32 v[32:33], v[34:35], v[36:37]
	s_and_b64 vcc, exec, s[0:1]
	v_pk_add_f32 v[30:31], v[30:31], v[32:33]
	s_nop 0
	v_add_f32_e32 v30, v30, v31
	ds_bpermute_b32 v31, v88, v30
	s_waitcnt lgkmcnt(0)
	v_add_f32_e32 v30, v30, v31
	ds_bpermute_b32 v31, v89, v30
	s_waitcnt lgkmcnt(0)
	v_add_f32_e32 v32, v30, v31
	ds_bpermute_b32 v33, v90, v32
	global_load_dwordx2 v[34:35], v[28:29], off offset:-1024 nt
	global_load_dwordx2 v[30:31], v[28:29], off offset:-512 nt
	global_load_dwordx2 v[82:83], v[22:23], off offset:-3584 nt
	global_load_dwordx2 v[66:67], v[22:23], off offset:-3072 nt
	global_load_dwordx2 v[46:47], v[22:23], off offset:-2560 nt
	global_load_dwordx2 v[42:43], v[22:23], off offset:-2048 nt
	global_load_dwordx2 v[74:75], v[28:29], off offset:-3072 nt
	global_load_dwordx2 v[50:51], v[28:29], off offset:-2560 nt
	global_load_dwordx2 v[44:45], v[28:29], off offset:-2048 nt
	global_load_dwordx2 v[40:41], v[28:29], off offset:-1536 nt
	s_waitcnt lgkmcnt(0)
	v_add_f32_e32 v32, v32, v33
	ds_bpermute_b32 v33, v91, v32
	s_waitcnt lgkmcnt(0)
	v_add_f32_e32 v32, v32, v33
	ds_bpermute_b32 v33, v92, v32
	s_waitcnt lgkmcnt(0)
	v_add_f32_e32 v96, v32, v33
	global_load_dwordx2 v[38:39], v[22:23], off offset:-1536 nt
	global_load_dwordx2 v[36:37], v[22:23], off offset:-1024 nt
	global_load_dwordx2 v[32:33], v[22:23], off offset:-512 nt
	global_load_dwordx2 v[28:29], v[22:23], off nt
	ds_bpermute_b32 v97, v93, v96
	s_waitcnt lgkmcnt(0)
	v_add_f32_e32 v96, v96, v97
	v_fmamk_f32 v85, v96, 0xba000000, v85
	v_fmamk_f32 v87, v96, 0xba000000, v87
	v_fmac_f32_e32 v84, 0xba000000, v96
	v_fmac_f32_e32 v86, 0xba000000, v96
	v_mul_f32_e32 v97, v87, v87
	v_mul_f32_e32 v98, v85, v85
	v_fmac_f32_e32 v97, v86, v86
	v_fmac_f32_e32 v98, v84, v84
	v_fmamk_f32 v63, v96, 0xba000000, v63
	v_fmamk_f32 v65, v96, 0xba000000, v65
	v_add_f32_e32 v97, v97, v98
	v_fmac_f32_e32 v62, 0xba000000, v96
	v_fmac_f32_e32 v64, 0xba000000, v96
	v_mul_f32_e32 v98, v65, v65
	v_mul_f32_e32 v99, v63, v63
	v_fmac_f32_e32 v98, v64, v64
	v_fmac_f32_e32 v99, v62, v62
	v_add_f32_e32 v98, v98, v99
	v_fmamk_f32 v55, v96, 0xba000000, v55
	v_fmamk_f32 v57, v96, 0xba000000, v57
	v_add_f32_e32 v97, v97, v98
	v_fmac_f32_e32 v54, 0xba000000, v96
	v_fmac_f32_e32 v56, 0xba000000, v96
	v_mul_f32_e32 v98, v57, v57
	v_mul_f32_e32 v99, v55, v55
	v_fmac_f32_e32 v98, v56, v56
	v_fmac_f32_e32 v99, v54, v54
	v_add_f32_e32 v98, v98, v99
	v_fmamk_f32 v49, v96, 0xba000000, v49
	v_fmamk_f32 v53, v96, 0xba000000, v53
	v_add_f32_e32 v97, v98, v97
	v_fmac_f32_e32 v48, 0xba000000, v96
	v_fmac_f32_e32 v52, 0xba000000, v96
	v_mul_f32_e32 v98, v53, v53
	v_mul_f32_e32 v99, v49, v49
	v_fmac_f32_e32 v98, v52, v52
	v_fmac_f32_e32 v99, v48, v48
	v_add_f32_e32 v98, v98, v99
	v_fmamk_f32 v59, v96, 0xba000000, v59
	v_fmamk_f32 v61, v96, 0xba000000, v61
	v_add_f32_e32 v97, v98, v97
	v_fmac_f32_e32 v58, 0xba000000, v96
	v_fmac_f32_e32 v60, 0xba000000, v96
	v_mul_f32_e32 v98, v61, v61
	v_mul_f32_e32 v99, v59, v59
	v_fmac_f32_e32 v98, v60, v60
	v_fmac_f32_e32 v99, v58, v58
	v_add_f32_e32 v98, v98, v99
	v_fmamk_f32 v69, v96, 0xba000000, v69
	v_fmamk_f32 v73, v96, 0xba000000, v73
	v_add_f32_e32 v97, v98, v97
	v_fmac_f32_e32 v68, 0xba000000, v96
	v_fmac_f32_e32 v72, 0xba000000, v96
	v_mul_f32_e32 v98, v73, v73
	v_mul_f32_e32 v99, v69, v69
	v_fmac_f32_e32 v98, v72, v72
	v_fmac_f32_e32 v99, v68, v68
	v_add_f32_e32 v98, v98, v99
	v_fmamk_f32 v71, v96, 0xba000000, v71
	v_fmamk_f32 v79, v96, 0xba000000, v79
	v_add_f32_e32 v97, v98, v97
	v_fmac_f32_e32 v70, 0xba000000, v96
	v_fmac_f32_e32 v78, 0xba000000, v96
	v_mul_f32_e32 v98, v79, v79
	v_mul_f32_e32 v99, v71, v71
	v_fmac_f32_e32 v98, v78, v78
	v_fmac_f32_e32 v99, v70, v70
	v_add_f32_e32 v98, v98, v99
	v_fmamk_f32 v77, v96, 0xba000000, v77
	v_fmamk_f32 v81, v96, 0xba000000, v81
	v_add_f32_e32 v97, v98, v97
	v_fmac_f32_e32 v76, 0xba000000, v96
	v_fmac_f32_e32 v80, 0xba000000, v96
	v_mul_f32_e32 v96, v81, v81
	v_mul_f32_e32 v98, v77, v77
	v_fmac_f32_e32 v96, v80, v80
	v_fmac_f32_e32 v98, v76, v76
	v_add_f32_e32 v96, v96, v98
	v_add_f32_e32 v96, v96, v97
	ds_bpermute_b32 v97, v88, v96
	s_waitcnt lgkmcnt(0)
	v_add_f32_e32 v96, v96, v97
	ds_bpermute_b32 v97, v89, v96
	s_waitcnt lgkmcnt(0)
	v_add_f32_e32 v96, v96, v97
	ds_bpermute_b32 v97, v90, v96
	s_waitcnt lgkmcnt(0)
	v_add_f32_e32 v96, v96, v97
	ds_bpermute_b32 v97, v91, v96
	s_waitcnt lgkmcnt(0)
	v_add_f32_e32 v96, v96, v97
	ds_bpermute_b32 v97, v92, v96
	s_waitcnt lgkmcnt(0)
	v_add_f32_e32 v96, v96, v97
	ds_bpermute_b32 v97, v93, v96
	s_cbranch_vccnz .Lln2_skip_a
	v_mov_b32_e32 v98, v160
	v_mov_b32_e32 v99, v161
	v_mov_b32_e32 v100, v162
	v_mov_b32_e32 v101, v163
	v_mov_b32_e32 v102, v164
	v_mov_b32_e32 v103, v165
	v_mov_b32_e32 v104, v166
	v_mov_b32_e32 v105, v167
	s_waitcnt lgkmcnt(0)
	v_add_f32_e32 v96, v96, v97
	v_fmamk_f32 v96, v96, 0x3a000000, v94
	v_mul_f32_e32 v97, 0x4f800000, v96
	v_cmp_gt_f32_e32 vcc, s14, v96
	s_nop 1
	v_cndmask_b32_e32 v96, v96, v97, vcc
	v_sqrt_f32_e32 v97, v96
	s_nop 0
	v_add_u32_e32 v106, -1, v97
	v_add_u32_e32 v107, 1, v97
	v_fma_f32 v108, -v106, v97, v96
	v_fma_f32 v109, -v107, v97, v96
	v_cmp_ge_f32_e64 s[2:3], 0, v108
	s_nop 1
	v_cndmask_b32_e64 v97, v97, v106, s[2:3]
	v_cmp_lt_f32_e64 s[2:3], 0, v109
	s_nop 1
	v_cndmask_b32_e64 v97, v97, v107, s[2:3]
	v_mul_f32_e32 v106, 0x37800000, v97
	v_cndmask_b32_e32 v97, v97, v106, vcc
	v_cmp_class_f32_e32 vcc, v96, v95
	s_nop 1
	v_cndmask_b32_e32 v106, v97, v96, vcc
	v_div_scale_f32 v107, s[2:3], v106, v106, 1.0
	v_rcp_f32_e32 v108, v107
	v_add_co_u32_e32 v96, vcc, s15, v20
	v_fma_f32 v110, -v107, v108, 1.0
	s_nop 0
	v_addc_co_u32_e32 v97, vcc, -1, v21, vcc
	v_div_scale_f32 v109, vcc, 1.0, v106, 1.0
	v_fmac_f32_e32 v108, v110, v108
	v_mul_f32_e32 v110, v109, v108
	v_fma_f32 v111, -v107, v110, v109
	v_fmac_f32_e32 v110, v111, v108
	v_fma_f32 v107, -v107, v110, v109
	v_div_fmas_f32 v107, v107, v108, v110
	v_div_fixup_f32 v106, v107, v106, 1.0
	v_pk_mul_f32 v[108:109], v[86:87], v[106:107] op_sel_hi:[1,0]
	v_pk_mul_f32 v[84:85], v[84:85], v[106:107] op_sel_hi:[1,0]
	v_pk_mul_f32 v[48:49], v[48:49], v[106:107] op_sel_hi:[1,0]
	v_pk_mul_f32 v[52:53], v[52:53], v[106:107] op_sel_hi:[1,0]
	s_waitcnt vmcnt(0)
	v_pk_fma_f32 v[86:87], v[84:85], v[100:101], v[104:105]
	v_pk_fma_f32 v[84:85], v[108:109], v[98:99], v[102:103]
	global_store_dwordx4 v[96:97], v[84:87], off nt
	s_nop 1
	v_mov_b32_e32 v84, v168
	v_mov_b32_e32 v85, v169
	v_mov_b32_e32 v86, v170
	v_mov_b32_e32 v87, v171
	s_nop 0
	v_mov_b32_e32 v96, v172
	v_mov_b32_e32 v97, v173
	v_mov_b32_e32 v98, v174
	v_mov_b32_e32 v99, v175
	v_add_co_u32_e32 v100, vcc, s5, v20
	v_pk_mul_f32 v[102:103], v[62:63], v[106:107] op_sel_hi:[1,0]
	v_pk_mul_f32 v[62:63], v[64:65], v[106:107] op_sel_hi:[1,0]
	v_addc_co_u32_e32 v101, vcc, -1, v21, vcc
	s_waitcnt vmcnt(1)
	v_pk_fma_f32 v[62:63], v[62:63], v[84:85], v[96:97]
	v_pk_fma_f32 v[64:65], v[102:103], v[86:87], v[98:99]
	global_store_dwordx4 v[100:101], v[62:65], off offset:-3072 nt
	s_nop 1
	v_mov_b32_e32 v62, v176
	v_mov_b32_e32 v63, v177
	v_mov_b32_e32 v64, v178
	v_mov_b32_e32 v65, v179
	s_nop 0
	v_mov_b32_e32 v84, v180
	v_mov_b32_e32 v85, v181
	v_mov_b32_e32 v86, v182
	v_mov_b32_e32 v87, v183
	v_pk_mul_f32 v[96:97], v[54:55], v[106:107] op_sel_hi:[1,0]
	v_pk_mul_f32 v[54:55], v[56:57], v[106:107] op_sel_hi:[1,0]
	s_waitcnt vmcnt(2)
	v_pk_fma_f32 v[56:57], v[96:97], v[64:65], v[86:87]
	v_pk_fma_f32 v[54:55], v[54:55], v[62:63], v[84:85]
	global_store_dwordx4 v[100:101], v[54:57], off offset:-2048 nt
	s_nop 1
	v_mov_b32_e32 v54, v184
	v_mov_b32_e32 v55, v185
	v_mov_b32_e32 v56, v186
	v_mov_b32_e32 v57, v187
	s_nop 0
	v_mov_b32_e32 v62, v188
	v_mov_b32_e32 v63, v189
	v_mov_b32_e32 v64, v190
	v_mov_b32_e32 v65, v191
	s_waitcnt vmcnt(3)
	v_pk_fma_f32 v[52:53], v[52:53], v[54:55], v[62:63]
	v_pk_fma_f32 v[54:55], v[48:49], v[56:57], v[64:65]
	global_store_dwordx4 v[100:101], v[52:55], off offset:-1024 nt
	s_nop 1
	v_mov_b32_e32 v52, v192
	v_mov_b32_e32 v53, v193
	v_mov_b32_e32 v54, v194
	v_mov_b32_e32 v55, v195
	s_nop 0
	v_mov_b32_e32 v62, v196
	v_mov_b32_e32 v63, v197
	v_mov_b32_e32 v64, v198
	v_mov_b32_e32 v65, v199
	v_pk_mul_f32 v[48:49], v[58:59], v[106:107] op_sel_hi:[1,0]
	v_pk_mul_f32 v[56:57], v[60:61], v[106:107] op_sel_hi:[1,0]
	v_pk_mul_f32 v[60:61], v[72:73], v[106:107] op_sel_hi:[1,0]
	s_waitcnt vmcnt(4)
	v_pk_fma_f32 v[52:53], v[56:57], v[52:53], v[62:63]
	v_pk_fma_f32 v[54:55], v[48:49], v[54:55], v[64:65]
	global_store_dwordx4 v[20:21], v[52:55], off offset:-4096 nt
	s_nop 1
	v_mov_b32_e32 v52, v200
	v_mov_b32_e32 v53, v201
	v_mov_b32_e32 v54, v202
	v_mov_b32_e32 v55, v203
	s_nop 0
	v_mov_b32_e32 v56, v204
	v_mov_b32_e32 v57, v205
	v_mov_b32_e32 v58, v206
	v_mov_b32_e32 v59, v207
	v_pk_mul_f32 v[48:49], v[68:69], v[106:107] op_sel_hi:[1,0]
	s_waitcnt vmcnt(5)
	v_pk_fma_f32 v[52:53], v[60:61], v[52:53], v[56:57]
	v_pk_fma_f32 v[54:55], v[48:49], v[54:55], v[58:59]
	global_store_dwordx4 v[20:21], v[52:55], off offset:-3072 nt
	s_nop 1
	v_mov_b32_e32 v52, v208
	v_mov_b32_e32 v53, v209
	v_mov_b32_e32 v54, v210
	v_mov_b32_e32 v55, v211
	s_nop 0
	v_mov_b32_e32 v56, v212
	v_mov_b32_e32 v57, v213
	v_mov_b32_e32 v58, v214
	v_mov_b32_e32 v59, v215
	v_pk_mul_f32 v[48:49], v[70:71], v[106:107] op_sel_hi:[1,0]
	v_pk_mul_f32 v[60:61], v[78:79], v[106:107] op_sel_hi:[1,0]
	s_waitcnt vmcnt(6)
	v_pk_fma_f32 v[54:55], v[48:49], v[54:55], v[58:59]
	v_pk_fma_f32 v[52:53], v[60:61], v[52:53], v[56:57]
	global_store_dwordx4 v[20:21], v[52:55], off offset:-2048 nt
	s_nop 1
	v_mov_b32_e32 v52, v216
	v_mov_b32_e32 v53, v217
	v_mov_b32_e32 v54, v218
	v_mov_b32_e32 v55, v219
	s_nop 0
	v_mov_b32_e32 v56, v220
	v_mov_b32_e32 v57, v221
	v_mov_b32_e32 v58, v222
	v_mov_b32_e32 v59, v223
	v_pk_mul_f32 v[48:49], v[76:77], v[106:107] op_sel_hi:[1,0]
	v_pk_mul_f32 v[60:61], v[80:81], v[106:107] op_sel_hi:[1,0]
	s_waitcnt vmcnt(7)
	v_pk_fma_f32 v[54:55], v[48:49], v[54:55], v[58:59]
	v_pk_fma_f32 v[52:53], v[60:61], v[52:53], v[56:57]
	global_store_dwordx4 v[20:21], v[52:55], off offset:-1024 nt
.LBB0_1284:
	s_nop 1
	v_lshlrev_b32_e32 v52, 16, v26
	v_and_b32_e32 v53, 0xffff0000, v26
	s_waitcnt vmcnt(8)
	v_lshlrev_b32_e32 v54, 16, v82
	v_and_b32_e32 v55, 0xffff0000, v82
	v_lshlrev_b32_e32 v26, 16, v27
	v_and_b32_e32 v27, 0xffff0000, v27
	v_lshlrev_b32_e32 v48, 16, v83
	v_and_b32_e32 v49, 0xffff0000, v83
	v_pk_fma_f32 v[54:55], v[52:53], s[12:13], v[54:55] op_sel_hi:[1,0,1]
	s_waitcnt vmcnt(8)
	v_lshlrev_b32_e32 v52, 16, v74
	v_and_b32_e32 v53, 0xffff0000, v74
	v_lshlrev_b32_e32 v56, 16, v66
	v_and_b32_e32 v57, 0xffff0000, v66
	v_pk_fma_f32 v[48:49], v[26:27], s[12:13], v[48:49] op_sel_hi:[1,0,1]
	v_lshlrev_b32_e32 v26, 16, v75
	v_and_b32_e32 v27, 0xffff0000, v75
	v_lshlrev_b32_e32 v58, 16, v67
	v_and_b32_e32 v59, 0xffff0000, v67
	v_pk_fma_f32 v[52:53], v[52:53], s[12:13], v[56:57] op_sel_hi:[1,0,1]
	v_pk_fma_f32 v[26:27], v[26:27], s[12:13], v[58:59] op_sel_hi:[1,0,1]
	v_mov_b32_e32 v56, v54
	v_mov_b32_e32 v57, v52
	v_mov_b32_e32 v58, v55
	v_mov_b32_e32 v59, v53
	v_pk_add_f32 v[56:57], v[56:57], v[58:59]
	v_mov_b32_e32 v58, v48
	v_mov_b32_e32 v59, v26
	v_mov_b32_e32 v60, v49
	v_mov_b32_e32 v61, v27
	v_pk_add_f32 v[58:59], v[58:59], v[60:61]
	v_lshlrev_b32_e32 v60, 16, v46
	v_pk_add_f32 v[56:57], v[56:57], v[58:59]
	s_waitcnt vmcnt(8)
	v_lshlrev_b32_e32 v58, 16, v50
	v_and_b32_e32 v59, 0xffff0000, v50
	v_lshlrev_b32_e32 v50, 16, v51
	v_and_b32_e32 v51, 0xffff0000, v51
	v_and_b32_e32 v61, 0xffff0000, v46
	v_lshlrev_b32_e32 v46, 16, v47
	v_and_b32_e32 v47, 0xffff0000, v47
	v_pk_fma_f32 v[46:47], v[50:51], s[12:13], v[46:47] op_sel_hi:[1,0,1]
	v_pk_fma_f32 v[50:51], v[58:59], s[12:13], v[60:61] op_sel_hi:[1,0,1]
	v_mov_b32_e32 v61, v47
	v_pk_mov_b32 v[58:59], v[50:51], v[46:47] op_sel:[1,0]
	v_mov_b32_e32 v60, v50
	v_pk_add_f32 v[58:59], v[58:59], v[60:61]
	s_waitcnt vmcnt(8)
	v_lshlrev_b32_e32 v60, 16, v44
	v_and_b32_e32 v61, 0xffff0000, v44
	v_lshlrev_b32_e32 v44, 16, v45
	v_and_b32_e32 v45, 0xffff0000, v45
	v_lshlrev_b32_e32 v62, 16, v42
	v_and_b32_e32 v63, 0xffff0000, v42
	v_lshlrev_b32_e32 v42, 16, v43
	v_and_b32_e32 v43, 0xffff0000, v43
	s_waitcnt vmcnt(8)
	v_lshlrev_b32_e32 v64, 16, v40
	v_and_b32_e32 v65, 0xffff0000, v40
	v_lshlrev_b32_e32 v40, 16, v41
	v_and_b32_e32 v41, 0xffff0000, v41
	s_waitcnt vmcnt(8)
	v_lshlrev_b32_e32 v66, 16, v38
	v_and_b32_e32 v67, 0xffff0000, v38
	v_lshlrev_b32_e32 v38, 16, v39
	v_and_b32_e32 v39, 0xffff0000, v39
	v_add_f32_e32 v56, 0, v56
	v_pk_add_f32 v[58:59], v[58:59], v[58:59] op_sel:[0,1] op_sel_hi:[1,0]
	v_pk_fma_f32 v[42:43], v[44:45], s[12:13], v[42:43] op_sel_hi:[1,0,1]
	v_pk_fma_f32 v[44:45], v[60:61], s[12:13], v[62:63] op_sel_hi:[1,0,1]
	v_pk_fma_f32 v[38:39], v[40:41], s[12:13], v[38:39] op_sel_hi:[1,0,1]
	v_pk_fma_f32 v[40:41], v[64:65], s[12:13], v[66:67] op_sel_hi:[1,0,1]
	v_add_f32_e32 v56, v56, v57
	v_add_f32_e32 v60, v44, v45
	v_add_f32_e32 v62, v42, v43
	v_mov_b32_e32 v57, v40
	v_mov_b32_e32 v59, v41
	v_mov_b32_e32 v61, v38
	v_mov_b32_e32 v63, v39
	v_pk_add_f32 v[56:57], v[56:57], v[58:59]
	v_pk_add_f32 v[58:59], v[60:61], v[62:63]
	s_waitcnt vmcnt(8)
	v_lshlrev_b32_e32 v60, 16, v36
	v_pk_add_f32 v[56:57], v[56:57], v[58:59]
	v_lshlrev_b32_e32 v58, 16, v34
	v_and_b32_e32 v59, 0xffff0000, v34
	v_lshlrev_b32_e32 v34, 16, v35
	v_and_b32_e32 v35, 0xffff0000, v35
	v_and_b32_e32 v61, 0xffff0000, v36
	v_lshlrev_b32_e32 v36, 16, v37
	v_and_b32_e32 v37, 0xffff0000, v37
	v_pk_fma_f32 v[34:35], v[34:35], s[12:13], v[36:37] op_sel_hi:[1,0,1]
	v_pk_fma_f32 v[36:37], v[58:59], s[12:13], v[60:61] op_sel_hi:[1,0,1]
	v_mov_b32_e32 v61, v35
	v_pk_mov_b32 v[58:59], v[36:37], v[34:35] op_sel:[1,0]
	v_mov_b32_e32 v60, v36
	v_pk_add_f32 v[58:59], v[58:59], v[60:61]
	v_lshlrev_b32_e32 v60, 16, v30
	v_and_b32_e32 v61, 0xffff0000, v30
	v_lshlrev_b32_e32 v30, 16, v31
	v_and_b32_e32 v31, 0xffff0000, v31
	s_waitcnt vmcnt(8)
	v_lshlrev_b32_e32 v62, 16, v32
	v_and_b32_e32 v63, 0xffff0000, v32
	v_lshlrev_b32_e32 v32, 16, v33
	v_and_b32_e32 v33, 0xffff0000, v33
	v_lshlrev_b32_e32 v64, 16, v24
	v_and_b32_e32 v65, 0xffff0000, v24
	v_lshlrev_b32_e32 v24, 16, v25
	v_and_b32_e32 v25, 0xffff0000, v25
	s_waitcnt vmcnt(8)
	v_lshlrev_b32_e32 v66, 16, v28
	v_and_b32_e32 v67, 0xffff0000, v28
	v_lshlrev_b32_e32 v28, 16, v29
	v_and_b32_e32 v29, 0xffff0000, v29
	v_pk_add_f32 v[56:57], v[56:57], v[56:57] op_sel:[0,1] op_sel_hi:[1,0]
	v_pk_add_f32 v[58:59], v[58:59], v[58:59] op_sel:[0,1] op_sel_hi:[1,0]
	v_pk_fma_f32 v[30:31], v[30:31], s[12:13], v[32:33] op_sel_hi:[1,0,1]
	v_pk_fma_f32 v[32:33], v[60:61], s[12:13], v[62:63] op_sel_hi:[1,0,1]
	v_pk_fma_f32 v[24:25], v[24:25], s[12:13], v[28:29] op_sel_hi:[1,0,1]
	v_pk_fma_f32 v[28:29], v[64:65], s[12:13], v[66:67] op_sel_hi:[1,0,1]
	v_add_f32_e32 v60, v32, v33
	v_add_f32_e32 v62, v30, v31
	v_mov_b32_e32 v57, v28
	v_mov_b32_e32 v59, v29
	v_mov_b32_e32 v61, v24
	v_mov_b32_e32 v63, v25
	v_pk_add_f32 v[56:57], v[56:57], v[58:59]
	v_pk_add_f32 v[58:59], v[60:61], v[62:63]
	s_and_b64 vcc, exec, s[0:1]
	v_pk_add_f32 v[56:57], v[56:57], v[58:59]
	s_nop 0
	v_add_f32_e32 v56, v56, v57
	ds_bpermute_b32 v57, v88, v56
	s_waitcnt lgkmcnt(0)
	v_add_f32_e32 v56, v56, v57
	ds_bpermute_b32 v57, v89, v56
	s_waitcnt lgkmcnt(0)
	v_add_f32_e32 v56, v56, v57
	ds_bpermute_b32 v57, v90, v56
	s_waitcnt lgkmcnt(0)
	v_add_f32_e32 v56, v56, v57
	ds_bpermute_b32 v57, v91, v56
	s_waitcnt lgkmcnt(0)
	v_add_f32_e32 v56, v56, v57
	ds_bpermute_b32 v57, v92, v56
	s_waitcnt lgkmcnt(0)
	v_add_f32_e32 v56, v56, v57
	ds_bpermute_b32 v57, v93, v56
	s_waitcnt lgkmcnt(0)
	v_add_f32_e32 v56, v56, v57
	v_fmamk_f32 v49, v56, 0xba000000, v49
	v_fmamk_f32 v55, v56, 0xba000000, v55
	v_fmac_f32_e32 v48, 0xba000000, v56
	v_fmac_f32_e32 v54, 0xba000000, v56
	v_mul_f32_e32 v57, v55, v55
	v_mul_f32_e32 v58, v49, v49
	v_fmac_f32_e32 v57, v54, v54
	v_fmac_f32_e32 v58, v48, v48
	v_fmamk_f32 v27, v56, 0xba000000, v27
	v_fmamk_f32 v53, v56, 0xba000000, v53
	v_add_f32_e32 v57, v57, v58
	v_fmac_f32_e32 v26, 0xba000000, v56
	v_fmac_f32_e32 v52, 0xba000000, v56
	v_mul_f32_e32 v58, v53, v53
	v_mul_f32_e32 v59, v27, v27
	v_fmac_f32_e32 v58, v52, v52
	v_fmac_f32_e32 v59, v26, v26
	v_add_f32_e32 v58, v58, v59
	v_fmamk_f32 v47, v56, 0xba000000, v47
	v_fmamk_f32 v51, v56, 0xba000000, v51
	v_add_f32_e32 v57, v57, v58
	v_fmac_f32_e32 v46, 0xba000000, v56
	v_fmac_f32_e32 v50, 0xba000000, v56
	v_mul_f32_e32 v58, v51, v51
	v_mul_f32_e32 v59, v47, v47
	v_fmac_f32_e32 v58, v50, v50
	v_fmac_f32_e32 v59, v46, v46
	v_add_f32_e32 v58, v58, v59
	v_fmamk_f32 v43, v56, 0xba000000, v43
	v_fmamk_f32 v45, v56, 0xba000000, v45
	v_add_f32_e32 v57, v58, v57
	v_fmac_f32_e32 v42, 0xba000000, v56
	v_fmac_f32_e32 v44, 0xba000000, v56
	v_mul_f32_e32 v58, v45, v45
	v_mul_f32_e32 v59, v43, v43
	v_fmac_f32_e32 v58, v44, v44
	v_fmac_f32_e32 v59, v42, v42
	v_add_f32_e32 v58, v58, v59
	v_fmamk_f32 v39, v56, 0xba000000, v39
	v_fmamk_f32 v41, v56, 0xba000000, v41
	v_add_f32_e32 v57, v58, v57
	v_fmac_f32_e32 v38, 0xba000000, v56
	v_fmac_f32_e32 v40, 0xba000000, v56
	v_mul_f32_e32 v58, v41, v41
	v_mul_f32_e32 v59, v39, v39
	v_fmac_f32_e32 v58, v40, v40
	v_fmac_f32_e32 v59, v38, v38
	v_add_f32_e32 v58, v58, v59
	v_fmamk_f32 v35, v56, 0xba000000, v35
	v_fmamk_f32 v37, v56, 0xba000000, v37
	v_add_f32_e32 v57, v58, v57
	v_fmac_f32_e32 v34, 0xba000000, v56
	v_fmac_f32_e32 v36, 0xba000000, v56
	v_mul_f32_e32 v58, v37, v37
	v_mul_f32_e32 v59, v35, v35
	v_fmac_f32_e32 v58, v36, v36
	v_fmac_f32_e32 v59, v34, v34
	v_add_f32_e32 v58, v58, v59
	v_fmamk_f32 v31, v56, 0xba000000, v31
	v_fmamk_f32 v33, v56, 0xba000000, v33
	v_add_f32_e32 v57, v58, v57
	v_fmac_f32_e32 v30, 0xba000000, v56
	v_fmac_f32_e32 v32, 0xba000000, v56
	v_mul_f32_e32 v58, v33, v33
	v_mul_f32_e32 v59, v31, v31
	v_fmac_f32_e32 v58, v32, v32
	v_fmac_f32_e32 v59, v30, v30
	v_add_f32_e32 v58, v58, v59
	v_fmamk_f32 v25, v56, 0xba000000, v25
	v_fmamk_f32 v29, v56, 0xba000000, v29
	v_add_f32_e32 v57, v58, v57
	v_fmac_f32_e32 v24, 0xba000000, v56
	v_fmac_f32_e32 v28, 0xba000000, v56
	v_mul_f32_e32 v56, v29, v29
	v_mul_f32_e32 v58, v25, v25
	v_fmac_f32_e32 v56, v28, v28
	v_fmac_f32_e32 v58, v24, v24
	v_add_f32_e32 v56, v56, v58
	v_add_f32_e32 v56, v56, v57
	ds_bpermute_b32 v57, v88, v56
	s_waitcnt lgkmcnt(0)
	v_add_f32_e32 v56, v56, v57
	ds_bpermute_b32 v57, v89, v56
	s_waitcnt lgkmcnt(0)
	v_add_f32_e32 v56, v56, v57
	ds_bpermute_b32 v57, v90, v56
	s_waitcnt lgkmcnt(0)
	v_add_f32_e32 v56, v56, v57
	ds_bpermute_b32 v57, v91, v56
	s_waitcnt lgkmcnt(0)
	v_add_f32_e32 v56, v56, v57
	ds_bpermute_b32 v57, v92, v56
	s_waitcnt lgkmcnt(0)
	v_add_f32_e32 v56, v56, v57
	ds_bpermute_b32 v57, v93, v56
	s_cbranch_vccnz .Lln2_skip_b
	v_mov_b32_e32 v58, v160
	v_mov_b32_e32 v59, v161
	v_mov_b32_e32 v60, v162
	v_mov_b32_e32 v61, v163
	v_mov_b32_e32 v62, v164
	v_mov_b32_e32 v63, v165
	v_mov_b32_e32 v64, v166
	v_mov_b32_e32 v65, v167
	s_waitcnt lgkmcnt(0)
	v_add_f32_e32 v56, v56, v57
	v_fmamk_f32 v56, v56, 0x3a000000, v94
	v_mul_f32_e32 v57, 0x4f800000, v56
	v_cmp_gt_f32_e32 vcc, s14, v56
	s_nop 1
	v_cndmask_b32_e32 v56, v56, v57, vcc
	v_sqrt_f32_e32 v57, v56
	s_nop 0
	v_add_u32_e32 v66, -1, v57
	v_add_u32_e32 v67, 1, v57
	v_fma_f32 v68, -v66, v57, v56
	v_fma_f32 v69, -v67, v57, v56
	v_cmp_ge_f32_e64 s[2:3], 0, v68
	s_nop 1
	v_cndmask_b32_e64 v57, v57, v66, s[2:3]
	v_cmp_lt_f32_e64 s[2:3], 0, v69
	s_nop 1
	v_cndmask_b32_e64 v57, v57, v67, s[2:3]
	v_mul_f32_e32 v66, 0x37800000, v57
	v_cndmask_b32_e32 v57, v57, v66, vcc
	v_cmp_class_f32_e32 vcc, v56, v95
	s_nop 1
	v_cndmask_b32_e32 v56, v57, v56, vcc
	v_div_scale_f32 v57, s[2:3], v56, v56, 1.0
	v_rcp_f32_e32 v66, v57
	v_div_scale_f32 v67, vcc, 1.0, v56, 1.0
	v_fma_f32 v68, -v57, v66, 1.0
	v_fmac_f32_e32 v66, v68, v66
	v_mul_f32_e32 v68, v67, v66
	v_fma_f32 v69, -v57, v68, v67
	v_fmac_f32_e32 v68, v69, v66
	v_fma_f32 v57, -v57, v68, v67
	v_div_fmas_f32 v57, v57, v66, v68
	v_div_fixup_f32 v66, v57, v56, 1.0
	v_pk_mul_f32 v[54:55], v[54:55], v[66:67] op_sel_hi:[1,0]
	v_pk_mul_f32 v[48:49], v[48:49], v[66:67] op_sel_hi:[1,0]
	v_pk_mul_f32 v[26:27], v[26:27], v[66:67] op_sel_hi:[1,0]
	s_waitcnt vmcnt(8)
	v_pk_fma_f32 v[56:57], v[48:49], v[60:61], v[64:65]
	v_pk_fma_f32 v[54:55], v[54:55], v[58:59], v[62:63]
	global_store_dwordx4 v[20:21], v[54:57], off nt
	s_nop 1
	v_mov_b32_e32 v54, v168
	v_mov_b32_e32 v55, v169
	v_mov_b32_e32 v56, v170
	v_mov_b32_e32 v57, v171
	s_nop 0
	v_mov_b32_e32 v58, v172
	v_mov_b32_e32 v59, v173
	v_mov_b32_e32 v60, v174
	v_mov_b32_e32 v61, v175
	v_pk_mul_f32 v[48:49], v[52:53], v[66:67] op_sel_hi:[1,0]
	s_waitcnt vmcnt(9)
	v_pk_fma_f32 v[52:53], v[48:49], v[54:55], v[58:59]
	v_pk_fma_f32 v[54:55], v[26:27], v[56:57], v[60:61]
	global_store_dwordx4 v[20:21], v[52:55], off offset:1024 nt
	s_nop 1
	v_mov_b32_e32 v52, v176
	v_mov_b32_e32 v53, v177
	v_mov_b32_e32 v54, v178
	v_mov_b32_e32 v55, v179
	s_nop 0
	v_mov_b32_e32 v56, v180
	v_mov_b32_e32 v57, v181
	v_mov_b32_e32 v58, v182
	v_mov_b32_e32 v59, v183
	v_pk_mul_f32 v[26:27], v[46:47], v[66:67] op_sel_hi:[1,0]
	v_pk_mul_f32 v[46:47], v[50:51], v[66:67] op_sel_hi:[1,0]
	s_waitcnt vmcnt(10)
	v_pk_fma_f32 v[48:49], v[26:27], v[54:55], v[58:59]
	v_pk_fma_f32 v[46:47], v[46:47], v[52:53], v[56:57]
	global_store_dwordx4 v[20:21], v[46:49], off offset:2048 nt
	s_nop 1
	v_mov_b32_e32 v46, v184
	v_mov_b32_e32 v47, v185
	v_mov_b32_e32 v48, v186
	v_mov_b32_e32 v49, v187
	s_nop 0
	v_mov_b32_e32 v50, v188
	v_mov_b32_e32 v51, v189
	v_mov_b32_e32 v52, v190
	v_mov_b32_e32 v53, v191
	v_pk_mul_f32 v[26:27], v[42:43], v[66:67] op_sel_hi:[1,0]
	v_pk_mul_f32 v[42:43], v[44:45], v[66:67] op_sel_hi:[1,0]
	s_waitcnt vmcnt(11)
	v_pk_fma_f32 v[44:45], v[26:27], v[48:49], v[52:53]
	v_pk_fma_f32 v[42:43], v[42:43], v[46:47], v[50:51]
	global_store_dwordx4 v[20:21], v[42:45], off offset:3072 nt
	s_nop 1
	v_mov_b32_e32 v42, v192
	v_mov_b32_e32 v43, v193
	v_mov_b32_e32 v44, v194
	v_mov_b32_e32 v45, v195
	s_nop 0
	v_mov_b32_e32 v46, v196
	v_mov_b32_e32 v47, v197
	v_mov_b32_e32 v48, v198
	v_mov_b32_e32 v49, v199
	v_add_co_u32_e32 v50, vcc, s13, v20
	v_pk_mul_f32 v[26:27], v[38:39], v[66:67] op_sel_hi:[1,0]
	v_pk_mul_f32 v[38:39], v[40:41], v[66:67] op_sel_hi:[1,0]
	v_addc_co_u32_e32 v51, vcc, 0, v21, vcc
	s_waitcnt vmcnt(12)
	v_pk_fma_f32 v[38:39], v[38:39], v[42:43], v[46:47]
	v_pk_fma_f32 v[40:41], v[26:27], v[44:45], v[48:49]
	global_store_dwordx4 v[50:51], v[38:41], off nt
	s_nop 1
	v_mov_b32_e32 v38, v200
	v_mov_b32_e32 v39, v201
	v_mov_b32_e32 v40, v202
	v_mov_b32_e32 v41, v203
	s_nop 0
	v_mov_b32_e32 v42, v204
	v_mov_b32_e32 v43, v205
	v_mov_b32_e32 v44, v206
	v_mov_b32_e32 v45, v207
	v_pk_mul_f32 v[26:27], v[34:35], v[66:67] op_sel_hi:[1,0]
	v_pk_mul_f32 v[34:35], v[36:37], v[66:67] op_sel_hi:[1,0]
	s_waitcnt vmcnt(13)
	v_pk_fma_f32 v[36:37], v[26:27], v[40:41], v[44:45]
	v_pk_fma_f32 v[34:35], v[34:35], v[38:39], v[42:43]
	global_store_dwordx4 v[50:51], v[34:37], off offset:1024 nt
	s_nop 1
	v_mov_b32_e32 v34, v208
	v_mov_b32_e32 v35, v209
	v_mov_b32_e32 v36, v210
	v_mov_b32_e32 v37, v211
	s_nop 0
	v_mov_b32_e32 v38, v212
	v_mov_b32_e32 v39, v213
	v_mov_b32_e32 v40, v214
	v_mov_b32_e32 v41, v215
	v_pk_mul_f32 v[26:27], v[30:31], v[66:67] op_sel_hi:[1,0]
	v_pk_mul_f32 v[30:31], v[32:33], v[66:67] op_sel_hi:[1,0]
	s_waitcnt vmcnt(14)
	v_pk_fma_f32 v[32:33], v[26:27], v[36:37], v[40:41]
	v_pk_fma_f32 v[30:31], v[30:31], v[34:35], v[38:39]
	global_store_dwordx4 v[50:51], v[30:33], off offset:2048 nt
	s_nop 1
	v_mov_b32_e32 v30, v216
	v_mov_b32_e32 v31, v217
	v_mov_b32_e32 v32, v218
	v_mov_b32_e32 v33, v219
	s_nop 0
	v_mov_b32_e32 v34, v220
	v_mov_b32_e32 v35, v221
	v_mov_b32_e32 v36, v222
	v_mov_b32_e32 v37, v223
	v_pk_mul_f32 v[26:27], v[24:25], v[66:67] op_sel_hi:[1,0]
	v_pk_mul_f32 v[24:25], v[28:29], v[66:67] op_sel_hi:[1,0]
	s_waitcnt vmcnt(15)
	v_pk_fma_f32 v[26:27], v[26:27], v[32:33], v[36:37]
	v_pk_fma_f32 v[24:25], v[24:25], v[30:31], v[34:35]
	global_store_dwordx4 v[50:51], v[24:27], off offset:3072 nt
	s_branch .LBB0_1281
.Lln2_skip_a:
	s_waitcnt vmcnt(0)
	s_branch .LBB0_1284
